# GEMM K loops: all s_setprio flips removed (no wave priority at all)
# speedup vs baseline: 1.0081x; 1.0007x over previous
.LBB0_118:
	ds_read_b128 v[128:131], v221
	ds_read_b128 v[132:135], v221 offset:1024
	ds_read_b128 v[136:139], v221 offset:2048
	ds_read_b128 v[140:143], v221 offset:3072
	s_add_u32 s8, s6, 0xfff80080
	s_addc_u32 s9, s7, -1
	s_cmp_eq_u32 s53, 28
	s_cselect_b32 s11, s5, s9
	s_cselect_b32 s10, s33, s8
	s_cselect_b32 s9, s43, s52
	s_cselect_b32 s8, s45, s51
	v_lshl_add_u64 v[198:199], s[6:7], 0, v[182:183]
	s_add_i32 m0, s58, 0xc000
	ds_read_b128 v[144:147], v222
	ds_read_b128 v[148:151], v222 offset:1024
	ds_read_b128 v[152:155], v222 offset:2048
	ds_read_b128 v[156:159], v222 offset:3072
	ds_read_b128 v[160:163], v222 offset:4096
	ds_read_b128 v[164:167], v222 offset:5120
	ds_read_b128 v[190:193], v222 offset:6144
	ds_read_b128 v[194:197], v222 offset:7168
	global_load_lds_dwordx4 v[198:199], off
	v_lshl_add_u64 v[198:199], s[6:7], 0, v[184:185]
	s_add_i32 m0, s58, 0xe000
	s_nop 0
	global_load_lds_dwordx4 v[198:199], off
	s_waitcnt lgkmcnt(8)
	s_barrier
	s_waitcnt lgkmcnt(0)

	s_waitcnt lgkmcnt(0)
	v_mfma_f32_16x16x32_bf16 v[124:127], v[128:131], v[144:147], v[124:127]
	v_mfma_f32_16x16x32_bf16 v[116:119], v[136:139], v[144:147], v[116:119]
	v_mfma_f32_16x16x32_bf16 v[108:111], v[128:131], v[152:155], v[108:111]
	v_mfma_f32_16x16x32_bf16 v[100:103], v[136:139], v[152:155], v[100:103]
	v_mfma_f32_16x16x32_bf16 v[92:95], v[128:131], v[160:163], v[92:95]
	v_mfma_f32_16x16x32_bf16 v[84:87], v[136:139], v[160:163], v[84:87]
	v_mfma_f32_16x16x32_bf16 v[76:79], v[128:131], v[190:193], v[76:79]
	v_mfma_f32_16x16x32_bf16 v[68:71], v[136:139], v[190:193], v[68:71]
	v_mfma_f32_16x16x32_bf16 v[124:127], v[132:135], v[148:151], v[124:127]
	v_mfma_f32_16x16x32_bf16 v[116:119], v[140:143], v[148:151], v[116:119]
	v_mfma_f32_16x16x32_bf16 v[108:111], v[132:135], v[156:159], v[108:111]
	v_mfma_f32_16x16x32_bf16 v[100:103], v[140:143], v[156:159], v[100:103]
	v_mfma_f32_16x16x32_bf16 v[92:95], v[132:135], v[164:167], v[92:95]
	v_mfma_f32_16x16x32_bf16 v[84:87], v[140:143], v[164:167], v[84:87]
	v_mfma_f32_16x16x32_bf16 v[76:79], v[132:135], v[194:197], v[76:79]
	v_mfma_f32_16x16x32_bf16 v[68:71], v[140:143], v[194:197], v[68:71]

	s_barrier
	s_add_i32 s54, s81, s57
	v_lshl_add_u64 v[230:231], s[8:9], 0, v[172:173]
	s_mov_b32 m0, s54
	ds_read_b128 v[198:201], v223
	ds_read_b128 v[202:205], v223 offset:1024
	ds_read_b128 v[206:209], v223 offset:2048
	ds_read_b128 v[226:229], v223 offset:3072
	global_load_lds_dwordx4 v[230:231], off
	v_lshl_add_u64 v[232:233], s[8:9], 0, v[174:175]
	s_add_i32 m0, s54, 0x2000
	s_nop 0
	global_load_lds_dwordx4 v[232:233], off
	s_barrier
	s_waitcnt lgkmcnt(0)

	s_waitcnt lgkmcnt(0)
	v_mfma_f32_16x16x32_bf16 v[120:123], v[198:201], v[144:147], v[120:123]
	v_mfma_f32_16x16x32_bf16 v[112:115], v[206:209], v[144:147], v[112:115]
	v_mfma_f32_16x16x32_bf16 v[104:107], v[198:201], v[152:155], v[104:107]
	v_mfma_f32_16x16x32_bf16 v[96:99], v[206:209], v[152:155], v[96:99]
	v_mfma_f32_16x16x32_bf16 v[88:91], v[198:201], v[160:163], v[88:91]
	v_mfma_f32_16x16x32_bf16 v[80:83], v[206:209], v[160:163], v[80:83]
	v_mfma_f32_16x16x32_bf16 v[72:75], v[198:201], v[190:193], v[72:75]
	v_mfma_f32_16x16x32_bf16 v[64:67], v[206:209], v[190:193], v[64:67]
	v_mfma_f32_16x16x32_bf16 v[120:123], v[202:205], v[148:151], v[120:123]
	v_mfma_f32_16x16x32_bf16 v[112:115], v[226:229], v[148:151], v[112:115]
	v_mfma_f32_16x16x32_bf16 v[104:107], v[202:205], v[156:159], v[104:107]
	v_mfma_f32_16x16x32_bf16 v[96:99], v[226:229], v[156:159], v[96:99]
	v_mfma_f32_16x16x32_bf16 v[88:91], v[202:205], v[164:167], v[88:91]
	v_mfma_f32_16x16x32_bf16 v[80:83], v[226:229], v[164:167], v[80:83]
	v_mfma_f32_16x16x32_bf16 v[72:75], v[202:205], v[194:197], v[72:75]
	v_mfma_f32_16x16x32_bf16 v[64:67], v[226:229], v[194:197], v[64:67]

	s_mov_b32 m0, s58
	v_lshl_add_u64 v[234:235], s[10:11], 0, v[172:173]
	s_barrier
	ds_read_b128 v[144:147], v222 offset:16384
	ds_read_b128 v[148:151], v222 offset:17408
	ds_read_b128 v[152:155], v222 offset:18432
	ds_read_b128 v[156:159], v222 offset:19456
	ds_read_b128 v[160:163], v222 offset:20480
	ds_read_b128 v[164:167], v222 offset:21504
	ds_read_b128 v[190:193], v222 offset:22528
	ds_read_b128 v[194:197], v222 offset:23552
	global_load_lds_dwordx4 v[234:235], off
	v_lshl_add_u64 v[236:237], s[10:11], 0, v[174:175]
	s_mov_b32 m0, s59
	s_nop 0
	global_load_lds_dwordx4 v[236:237], off
	s_barrier
	s_waitcnt lgkmcnt(0)

	s_waitcnt lgkmcnt(0)
	v_mfma_f32_16x16x32_bf16 v[60:63], v[128:131], v[144:147], v[60:63]
	v_mfma_f32_16x16x32_bf16 v[52:55], v[136:139], v[144:147], v[52:55]
	v_mfma_f32_16x16x32_bf16 v[44:47], v[128:131], v[152:155], v[44:47]
	v_mfma_f32_16x16x32_bf16 v[36:39], v[136:139], v[152:155], v[36:39]
	v_mfma_f32_16x16x32_bf16 v[28:31], v[128:131], v[160:163], v[28:31]
	v_mfma_f32_16x16x32_bf16 v[20:23], v[136:139], v[160:163], v[20:23]
	v_mfma_f32_16x16x32_bf16 v[12:15], v[128:131], v[190:193], v[12:15]
	v_mfma_f32_16x16x32_bf16 v[4:7], v[136:139], v[190:193], v[4:7]
	v_mfma_f32_16x16x32_bf16 v[60:63], v[132:135], v[148:151], v[60:63]
	v_mfma_f32_16x16x32_bf16 v[52:55], v[140:143], v[148:151], v[52:55]
	v_mfma_f32_16x16x32_bf16 v[44:47], v[132:135], v[156:159], v[44:47]
	v_mfma_f32_16x16x32_bf16 v[36:39], v[140:143], v[156:159], v[36:39]
	v_mfma_f32_16x16x32_bf16 v[28:31], v[132:135], v[164:167], v[28:31]
	v_mfma_f32_16x16x32_bf16 v[20:23], v[140:143], v[164:167], v[20:23]
	v_mfma_f32_16x16x32_bf16 v[12:15], v[132:135], v[194:197], v[12:15]
	v_mfma_f32_16x16x32_bf16 v[4:7], v[140:143], v[194:197], v[4:7]

	s_barrier
	s_add_u32 s54, s8, 0x80000
	s_addc_u32 s55, s9, 0
	s_add_i32 vcc_lo, s30, s57
	v_lshl_add_u64 v[128:129], s[54:55], 0, v[172:173]
	s_mov_b32 m0, vcc_lo
	s_nop 0
	global_load_lds_dwordx4 v[128:129], off
	v_lshl_add_u64 v[128:129], s[54:55], 0, v[174:175]
	s_add_i32 m0, vcc_lo, 0x2000
	s_nop 0
	global_load_lds_dwordx4 v[128:129], off
	s_waitcnt vmcnt(6)
	s_barrier

	v_mfma_f32_16x16x32_bf16 v[56:59], v[198:201], v[144:147], v[56:59]
	v_mfma_f32_16x16x32_bf16 v[48:51], v[206:209], v[144:147], v[48:51]
	v_mfma_f32_16x16x32_bf16 v[40:43], v[198:201], v[152:155], v[40:43]
	v_mfma_f32_16x16x32_bf16 v[32:35], v[206:209], v[152:155], v[32:35]
	v_mfma_f32_16x16x32_bf16 v[24:27], v[198:201], v[160:163], v[24:27]
	v_mfma_f32_16x16x32_bf16 v[16:19], v[206:209], v[160:163], v[16:19]
	v_mfma_f32_16x16x32_bf16 v[8:11], v[198:201], v[190:193], v[8:11]
	v_mfma_f32_16x16x32_bf16 v[0:3], v[206:209], v[190:193], v[0:3]
	v_mfma_f32_16x16x32_bf16 v[56:59], v[202:205], v[148:151], v[56:59]
	v_mfma_f32_16x16x32_bf16 v[48:51], v[226:229], v[148:151], v[48:51]
	v_mfma_f32_16x16x32_bf16 v[40:43], v[202:205], v[156:159], v[40:43]
	v_mfma_f32_16x16x32_bf16 v[32:35], v[226:229], v[156:159], v[32:35]
	v_mfma_f32_16x16x32_bf16 v[24:27], v[202:205], v[164:167], v[24:27]
	v_mfma_f32_16x16x32_bf16 v[16:19], v[226:229], v[164:167], v[16:19]
	v_mfma_f32_16x16x32_bf16 v[8:11], v[202:205], v[194:197], v[8:11]
	v_mfma_f32_16x16x32_bf16 v[0:3], v[226:229], v[194:197], v[0:3]

	s_add_i32 s54, 0, 0x18000
	v_add_u32_e32 v140, s54, v179
	s_barrier
	ds_read_b128 v[128:131], v140
	ds_read_b128 v[132:135], v140 offset:1024
	ds_read_b128 v[136:139], v140 offset:2048
	ds_read_b128 v[140:143], v140 offset:3072
	s_add_u32 s10, s10, 0x80000
	s_addc_u32 s11, s11, 0
	s_mov_b32 m0, s2
	v_lshl_add_u64 v[198:199], s[10:11], 0, v[172:173]
	ds_read_b128 v[144:147], v222 offset:32768
	ds_read_b128 v[148:151], v222 offset:33792
	ds_read_b128 v[152:155], v222 offset:34816
	ds_read_b128 v[156:159], v222 offset:35840
	ds_read_b128 v[160:163], v222 offset:36864
	ds_read_b128 v[164:167], v222 offset:37888
	ds_read_b128 v[190:193], v222 offset:38912
	ds_read_b128 v[194:197], v222 offset:39936
	global_load_lds_dwordx4 v[198:199], off
	v_lshl_add_u64 v[198:199], s[10:11], 0, v[174:175]
	s_mov_b32 m0, s3
	s_nop 0
	global_load_lds_dwordx4 v[198:199], off
	s_waitcnt lgkmcnt(8)
	s_barrier
	s_waitcnt lgkmcnt(0)

	s_waitcnt lgkmcnt(0)
	v_mfma_f32_16x16x32_bf16 v[124:127], v[128:131], v[144:147], v[124:127]
	v_mfma_f32_16x16x32_bf16 v[116:119], v[136:139], v[144:147], v[116:119]
	v_mfma_f32_16x16x32_bf16 v[108:111], v[128:131], v[152:155], v[108:111]
	v_mfma_f32_16x16x32_bf16 v[100:103], v[136:139], v[152:155], v[100:103]
	v_mfma_f32_16x16x32_bf16 v[92:95], v[128:131], v[160:163], v[92:95]
	v_mfma_f32_16x16x32_bf16 v[84:87], v[136:139], v[160:163], v[84:87]
	v_mfma_f32_16x16x32_bf16 v[76:79], v[128:131], v[190:193], v[76:79]
	v_mfma_f32_16x16x32_bf16 v[68:71], v[136:139], v[190:193], v[68:71]
	v_mfma_f32_16x16x32_bf16 v[124:127], v[132:135], v[148:151], v[124:127]
	v_mfma_f32_16x16x32_bf16 v[116:119], v[140:143], v[148:151], v[116:119]
	v_mfma_f32_16x16x32_bf16 v[108:111], v[132:135], v[156:159], v[108:111]
	v_mfma_f32_16x16x32_bf16 v[100:103], v[140:143], v[156:159], v[100:103]
	v_mfma_f32_16x16x32_bf16 v[92:95], v[132:135], v[164:167], v[92:95]
	v_mfma_f32_16x16x32_bf16 v[84:87], v[140:143], v[164:167], v[84:87]
	v_mfma_f32_16x16x32_bf16 v[76:79], v[132:135], v[194:197], v[76:79]
	v_mfma_f32_16x16x32_bf16 v[68:71], v[140:143], v[194:197], v[68:71]

	s_barrier
	s_add_i32 s10, 0, 0x1c000
	s_add_i32 s11, s54, s57
	v_add_u32_e32 v180, s10, v179
	v_lshl_add_u64 v[230:231], v[230:231], 0, s[20:21]
	s_mov_b32 m0, s11
	ds_read_b128 v[198:201], v180
	ds_read_b128 v[202:205], v180 offset:1024
	ds_read_b128 v[206:209], v180 offset:2048
	ds_read_b128 v[226:229], v180 offset:3072
	global_load_lds_dwordx4 v[230:231], off
	v_lshl_add_u64 v[230:231], v[232:233], 0, s[20:21]
	s_add_i32 m0, s11, 0x2000
	s_nop 0
	global_load_lds_dwordx4 v[230:231], off
	s_barrier
	s_waitcnt lgkmcnt(0)

	s_waitcnt lgkmcnt(0)
	v_mfma_f32_16x16x32_bf16 v[120:123], v[198:201], v[144:147], v[120:123]
	v_mfma_f32_16x16x32_bf16 v[112:115], v[206:209], v[144:147], v[112:115]
	v_mfma_f32_16x16x32_bf16 v[104:107], v[198:201], v[152:155], v[104:107]
	v_mfma_f32_16x16x32_bf16 v[96:99], v[206:209], v[152:155], v[96:99]
	v_mfma_f32_16x16x32_bf16 v[88:91], v[198:201], v[160:163], v[88:91]
	v_mfma_f32_16x16x32_bf16 v[80:83], v[206:209], v[160:163], v[80:83]
	v_mfma_f32_16x16x32_bf16 v[72:75], v[198:201], v[190:193], v[72:75]
	v_mfma_f32_16x16x32_bf16 v[64:67], v[206:209], v[190:193], v[64:67]
	v_mfma_f32_16x16x32_bf16 v[120:123], v[202:205], v[148:151], v[120:123]
	v_mfma_f32_16x16x32_bf16 v[112:115], v[226:229], v[148:151], v[112:115]
	v_mfma_f32_16x16x32_bf16 v[104:107], v[202:205], v[156:159], v[104:107]
	v_mfma_f32_16x16x32_bf16 v[96:99], v[226:229], v[156:159], v[96:99]
	v_mfma_f32_16x16x32_bf16 v[88:91], v[202:205], v[164:167], v[88:91]
	v_mfma_f32_16x16x32_bf16 v[80:83], v[226:229], v[164:167], v[80:83]
	v_mfma_f32_16x16x32_bf16 v[72:75], v[202:205], v[194:197], v[72:75]
	v_mfma_f32_16x16x32_bf16 v[64:67], v[226:229], v[194:197], v[64:67]

	s_mov_b32 m0, s96
	v_lshl_add_u64 v[230:231], v[234:235], 0, s[20:21]
	s_barrier
	ds_read_b128 v[144:147], v222 offset:49152
	ds_read_b128 v[148:151], v222 offset:50176
	ds_read_b128 v[152:155], v222 offset:51200
	ds_read_b128 v[156:159], v222 offset:52224
	ds_read_b128 v[160:163], v222 offset:53248
	ds_read_b128 v[164:167], v222 offset:54272
	ds_read_b128 v[190:193], v222 offset:55296
	ds_read_b128 v[194:197], v222 offset:56320
	global_load_lds_dwordx4 v[230:231], off
	v_lshl_add_u64 v[230:231], v[236:237], 0, s[20:21]
	s_mov_b32 m0, s97
	s_nop 0
	global_load_lds_dwordx4 v[230:231], off
	s_barrier
	s_waitcnt lgkmcnt(0)

	s_waitcnt lgkmcnt(0)
	v_mfma_f32_16x16x32_bf16 v[60:63], v[128:131], v[144:147], v[60:63]
	v_mfma_f32_16x16x32_bf16 v[52:55], v[136:139], v[144:147], v[52:55]
	v_mfma_f32_16x16x32_bf16 v[44:47], v[128:131], v[152:155], v[44:47]
	v_mfma_f32_16x16x32_bf16 v[36:39], v[136:139], v[152:155], v[36:39]
	v_mfma_f32_16x16x32_bf16 v[28:31], v[128:131], v[160:163], v[28:31]
	v_mfma_f32_16x16x32_bf16 v[20:23], v[136:139], v[160:163], v[20:23]
	v_mfma_f32_16x16x32_bf16 v[12:15], v[128:131], v[190:193], v[12:15]
	v_mfma_f32_16x16x32_bf16 v[4:7], v[136:139], v[190:193], v[4:7]
	v_mfma_f32_16x16x32_bf16 v[60:63], v[132:135], v[148:151], v[60:63]
	v_mfma_f32_16x16x32_bf16 v[52:55], v[140:143], v[148:151], v[52:55]
	v_mfma_f32_16x16x32_bf16 v[44:47], v[132:135], v[156:159], v[44:47]
	v_mfma_f32_16x16x32_bf16 v[36:39], v[140:143], v[156:159], v[36:39]
	v_mfma_f32_16x16x32_bf16 v[28:31], v[132:135], v[164:167], v[28:31]
	v_mfma_f32_16x16x32_bf16 v[20:23], v[140:143], v[164:167], v[20:23]
	v_mfma_f32_16x16x32_bf16 v[12:15], v[132:135], v[194:197], v[12:15]
	v_mfma_f32_16x16x32_bf16 v[4:7], v[140:143], v[194:197], v[4:7]

	s_barrier
	s_add_u32 s8, s8, 0x80080
	s_addc_u32 s9, s9, 0
	s_add_i32 s10, s10, s57
	v_lshl_add_u64 v[128:129], s[8:9], 0, v[172:173]
	s_mov_b32 m0, s10
	s_nop 0
	global_load_lds_dwordx4 v[128:129], off
	v_lshl_add_u64 v[128:129], s[8:9], 0, v[174:175]
	s_add_i32 m0, s10, 0x2000
	s_nop 0
	global_load_lds_dwordx4 v[128:129], off
	s_waitcnt vmcnt(6)
	s_barrier

	v_mfma_f32_16x16x32_bf16 v[56:59], v[198:201], v[144:147], v[56:59]
	v_mfma_f32_16x16x32_bf16 v[48:51], v[206:209], v[144:147], v[48:51]
	v_mfma_f32_16x16x32_bf16 v[40:43], v[198:201], v[152:155], v[40:43]
	v_mfma_f32_16x16x32_bf16 v[32:35], v[206:209], v[152:155], v[32:35]
	v_mfma_f32_16x16x32_bf16 v[24:27], v[198:201], v[160:163], v[24:27]
	v_mfma_f32_16x16x32_bf16 v[16:19], v[206:209], v[160:163], v[16:19]
	v_mfma_f32_16x16x32_bf16 v[8:11], v[198:201], v[190:193], v[8:11]
	v_mfma_f32_16x16x32_bf16 v[0:3], v[206:209], v[190:193], v[0:3]
	v_mfma_f32_16x16x32_bf16 v[56:59], v[202:205], v[148:151], v[56:59]
	v_mfma_f32_16x16x32_bf16 v[48:51], v[226:229], v[148:151], v[48:51]
	v_mfma_f32_16x16x32_bf16 v[40:43], v[202:205], v[156:159], v[40:43]
	v_mfma_f32_16x16x32_bf16 v[32:35], v[226:229], v[156:159], v[32:35]
	v_mfma_f32_16x16x32_bf16 v[24:27], v[202:205], v[164:167], v[24:27]
	v_mfma_f32_16x16x32_bf16 v[16:19], v[226:229], v[164:167], v[16:19]
	v_mfma_f32_16x16x32_bf16 v[8:11], v[202:205], v[194:197], v[8:11]
	v_mfma_f32_16x16x32_bf16 v[0:3], v[226:229], v[194:197], v[0:3]

	s_add_i32 s53, s53, 2
	s_add_u32 s6, s6, 0x100
	s_addc_u32 s7, s7, 0
	s_add_u32 s51, s51, 0x100
	s_addc_u32 s52, s52, 0
	s_cmp_gt_u32 s53, 29
	s_barrier
	s_cbranch_scc0 .LBB0_118
	v_mov_b32_e32 v142, v210
	v_mov_b32_e32 v143, v169
	s_lshl_b32 s33, s4, 8
	s_add_i32 s33, s33, s34
	v_lshl_add_u32 v133, v142, 4, v143
	v_ashrrev_i32_e32 v198, 2, v133
	v_and_b32_e32 v192, 3, v143
	v_and_b32_e32 v128, -4, v133
	s_cmp_gt_i32 s4, 30
	v_lshl_add_u32 v226, v192, 6, v128
	v_add_u32_e32 v190, s33, v198
	s_cselect_b64 s[52:53], -1, 0
	s_cmp_gt_i32 s50, 8
	s_mov_b64 s[4:5], -1
	s_cbranch_scc0 .LBB0_419
	s_cmp_lg_u32 s50, 9
	s_cbranch_scc0 .LBB0_225
	s_cmp_gt_u32 s50, 25
	s_cbranch_scc0 .LBB0_127
	v_mul_f32_e32 v130, 0xbfb8aa3b, v120
	v_mul_f32_e32 v131, 0xbfb8aa3b, v121
	v_mul_f32_e32 v132, 0xbfb8aa3b, v122
	v_mul_f32_e32 v134, 0xbfb8aa3b, v123
	v_mul_f32_e32 v135, 0xbfb8aa3b, v112
	v_mul_f32_e32 v136, 0xbfb8aa3b, v113
	v_mul_f32_e32 v137, 0xbfb8aa3b, v114
	v_mul_f32_e32 v138, 0xbfb8aa3b, v115
	v_mul_f32_e32 v139, 0xbfb8aa3b, v104
	v_mul_f32_e32 v140, 0xbfb8aa3b, v105
	v_mul_f32_e32 v141, 0xbfb8aa3b, v106
	v_mul_f32_e32 v144, 0xbfb8aa3b, v107
	v_mul_f32_e32 v145, 0xbfb8aa3b, v96
	v_mul_f32_e32 v146, 0xbfb8aa3b, v97
	v_mul_f32_e32 v147, 0xbfb8aa3b, v98
	v_mul_f32_e32 v148, 0xbfb8aa3b, v99
	v_mul_f32_e32 v149, 0xbfb8aa3b, v88
	v_mul_f32_e32 v150, 0xbfb8aa3b, v89
	v_mul_f32_e32 v151, 0xbfb8aa3b, v90
	v_mul_f32_e32 v152, 0xbfb8aa3b, v91
	v_mul_f32_e32 v153, 0xbfb8aa3b, v80
	v_mul_f32_e32 v154, 0xbfb8aa3b, v81
	v_mul_f32_e32 v155, 0xbfb8aa3b, v82
	v_mul_f32_e32 v180, 0xbfb8aa3b, v83
	v_mul_f32_e32 v206, 0xbfb8aa3b, v72
	v_mul_f32_e32 v207, 0xbfb8aa3b, v73
	v_mul_f32_e32 v208, 0xbfb8aa3b, v74
	v_mul_f32_e32 v209, 0xbfb8aa3b, v75
	v_mul_f32_e32 v227, 0xbfb8aa3b, v64
	v_mul_f32_e32 v228, 0xbfb8aa3b, v65
	v_mul_f32_e32 v229, 0xbfb8aa3b, v66
	v_mul_f32_e32 v230, 0xbfb8aa3b, v67
	v_exp_f32_e32 v205, v130
	v_exp_f32_e32 v204, v131
	v_exp_f32_e32 v203, v132
	v_exp_f32_e32 v202, v134
	v_exp_f32_e32 v200, v135
	v_exp_f32_e32 v199, v136
	v_exp_f32_e32 v197, v137
	v_exp_f32_e32 v196, v138
	v_exp_f32_e32 v195, v139
	v_exp_f32_e32 v194, v140
	v_exp_f32_e32 v193, v141
	v_exp_f32_e32 v167, v144
	v_exp_f32_e32 v166, v145
	v_exp_f32_e32 v165, v146
	v_exp_f32_e32 v164, v147
	v_exp_f32_e32 v163, v148
	v_exp_f32_e32 v162, v149
	v_exp_f32_e32 v161, v150
	v_exp_f32_e32 v160, v151
	v_exp_f32_e32 v159, v152
	v_exp_f32_e32 v158, v153
	v_exp_f32_e32 v157, v154
	v_exp_f32_e32 v156, v155
	v_exp_f32_e32 v155, v180
	v_exp_f32_e32 v154, v206
	v_exp_f32_e32 v153, v207
	v_exp_f32_e32 v152, v208
	v_exp_f32_e32 v151, v209
	v_exp_f32_e32 v150, v227
	v_exp_f32_e32 v149, v228
	v_exp_f32_e32 v148, v229
	v_exp_f32_e32 v147, v230
	v_ashrrev_i32_e32 v191, 31, v190
	s_cmp_lt_u32 s50, 42
	v_lshlrev_b32_e32 v201, 2, v192
	v_lshlrev_b64 v[128:129], 12, v[190:191]
	v_mul_f32_e32 v146, 0xbfb8aa3b, v56
	v_mul_f32_e32 v145, 0xbfb8aa3b, v57
	v_mul_f32_e32 v144, 0xbfb8aa3b, v58
	v_mul_f32_e32 v141, 0xbfb8aa3b, v59
	v_mul_f32_e32 v140, 0xbfb8aa3b, v48
	v_mul_f32_e32 v139, 0xbfb8aa3b, v49
	v_mul_f32_e32 v138, 0xbfb8aa3b, v50
	v_mul_f32_e32 v137, 0xbfb8aa3b, v51
	v_mul_f32_e32 v136, 0xbfb8aa3b, v40
	v_mul_f32_e32 v135, 0xbfb8aa3b, v41
	v_mul_f32_e32 v134, 0xbfb8aa3b, v42
	v_mul_f32_e32 v132, 0xbfb8aa3b, v43
	s_cbranch_scc1 .LBB0_124
	v_mul_f32_e32 v130, 0xbfb8aa3b, v124
	v_mul_f32_e32 v131, 0xbfb8aa3b, v125
	v_mul_f32_e32 v206, 0xbfb8aa3b, v126
	v_mul_f32_e32 v207, 0xbfb8aa3b, v127
	v_exp_f32_e32 v130, v130
	v_exp_f32_e32 v131, v131
	v_exp_f32_e32 v206, v206
	v_exp_f32_e32 v207, v207
	v_add_f32_e32 v130, 1.0, v130
	v_add_f32_e32 v131, 1.0, v131
	v_add_f32_e32 v206, 1.0, v206
	v_add_f32_e32 v207, 1.0, v207
	v_rcp_f32_e32 v130, v130
	v_rcp_f32_e32 v131, v131
	v_rcp_f32_e32 v206, v206
	v_rcp_f32_e32 v207, v207
	s_lshl_b32 s4, s50, 8
	v_cvt_pk_bf16_f32 v130, v130, v131
	s_add_i32 s4, s28, s4
	v_cvt_pk_bf16_f32 v131, v206, v207
	ds_bpermute_b32 v206, v226, v130
	ds_bpermute_b32 v207, v226, v131
	v_or_b32_e32 v180, s4, v201
	v_lshl_add_u64 v[130:131], s[40:41], 0, v[128:129]
	v_lshlrev_b64 v[208:209], 1, v[180:181]
	v_lshl_add_u64 v[130:131], v[130:131], 0, v[208:209]
	s_waitcnt lgkmcnt(0)
	global_store_dwordx2 v[130:131], v[206:207], off
	v_mul_f32_e32 v180, 0xbfb8aa3b, v116
	v_mul_f32_e32 v206, 0xbfb8aa3b, v117
	v_mul_f32_e32 v207, 0xbfb8aa3b, v118
	v_mul_f32_e32 v208, 0xbfb8aa3b, v119
	v_exp_f32_e32 v180, v180
	v_exp_f32_e32 v206, v206
	v_exp_f32_e32 v207, v207
	v_exp_f32_e32 v208, v208
	v_add_f32_e32 v180, 1.0, v180
	v_add_f32_e32 v206, 1.0, v206
	v_add_f32_e32 v207, 1.0, v207
	v_add_f32_e32 v208, 1.0, v208
	v_rcp_f32_e32 v180, v180
	v_rcp_f32_e32 v206, v206
	v_rcp_f32_e32 v207, v207
	v_rcp_f32_e32 v208, v208
	s_mov_b64 s[4:5], 0x10000
	v_cvt_pk_bf16_f32 v180, v180, v206
	ds_bpermute_b32 v206, v226, v180
	v_cvt_pk_bf16_f32 v207, v207, v208
	ds_bpermute_b32 v207, v226, v207
	v_add_f32_e32 v180, 1.0, v205
	v_add_f32_e32 v208, 1.0, v202
	v_rcp_f32_e32 v180, v180
	v_rcp_f32_e32 v208, v208
	s_waitcnt lgkmcnt(0)
	global_store_dwordx2 v[130:131], v[206:207], off offset:32
	v_add_f32_e32 v206, 1.0, v204
	v_add_f32_e32 v207, 1.0, v203
	v_rcp_f32_e32 v206, v206
	v_rcp_f32_e32 v207, v207
	v_mul_f32_e32 v227, 0xbfb8aa3b, v103
	v_exp_f32_e32 v227, v227
	v_cvt_pk_bf16_f32 v180, v180, v206
	v_cvt_pk_bf16_f32 v207, v207, v208
	ds_bpermute_b32 v206, v226, v180
	ds_bpermute_b32 v207, v226, v207
	v_add_f32_e32 v180, 1.0, v200
	v_add_f32_e32 v208, 1.0, v196
	v_rcp_f32_e32 v180, v180
	v_rcp_f32_e32 v208, v208
	s_waitcnt lgkmcnt(0)
	global_store_dwordx2 v[130:131], v[206:207], off offset:256
	v_add_f32_e32 v206, 1.0, v199
	v_add_f32_e32 v207, 1.0, v197
	v_rcp_f32_e32 v206, v206
	v_rcp_f32_e32 v207, v207
	v_add_f32_e32 v227, 1.0, v227
	v_rcp_f32_e32 v227, v227
	v_cvt_pk_bf16_f32 v180, v180, v206
	v_cvt_pk_bf16_f32 v207, v207, v208
	ds_bpermute_b32 v206, v226, v180
	ds_bpermute_b32 v207, v226, v207
	v_mul_f32_e32 v180, 0xbfb8aa3b, v108
	v_mul_f32_e32 v208, 0xbfb8aa3b, v111
	v_exp_f32_e32 v180, v180
	v_exp_f32_e32 v208, v208
	s_waitcnt lgkmcnt(0)
	global_store_dwordx2 v[130:131], v[206:207], off offset:288
	v_mul_f32_e32 v206, 0xbfb8aa3b, v109
	v_mul_f32_e32 v207, 0xbfb8aa3b, v110
	v_exp_f32_e32 v206, v206
	v_exp_f32_e32 v207, v207
	v_add_f32_e32 v180, 1.0, v180
	v_add_f32_e32 v208, 1.0, v208
	v_add_f32_e32 v206, 1.0, v206
	v_add_f32_e32 v207, 1.0, v207
	v_rcp_f32_e32 v180, v180
	v_rcp_f32_e32 v206, v206
	v_rcp_f32_e32 v207, v207
	v_rcp_f32_e32 v208, v208
	v_cvt_pk_bf16_f32 v180, v180, v206
	ds_bpermute_b32 v206, v226, v180
	v_cvt_pk_bf16_f32 v207, v207, v208
	ds_bpermute_b32 v207, v226, v207
	v_lshl_add_u64 v[208:209], v[130:131], 0, s[4:5]
	s_mov_b32 s4, 0x10000
	v_add_co_u32_e32 v228, vcc, s4, v130
	v_mul_f32_e32 v180, 0xbfb8aa3b, v100
	s_nop 0
	v_addc_co_u32_e32 v229, vcc, 0, v131, vcc
	s_waitcnt lgkmcnt(0)
	global_store_dwordx2 v[228:229], v[206:207], off
	v_mul_f32_e32 v206, 0xbfb8aa3b, v101
	v_mul_f32_e32 v207, 0xbfb8aa3b, v102
	v_exp_f32_e32 v180, v180
	v_exp_f32_e32 v206, v206
	v_exp_f32_e32 v207, v207
	s_mov_b64 s[4:5], 0x20000
	v_add_f32_e32 v180, 1.0, v180
	v_add_f32_e32 v206, 1.0, v206
	v_add_f32_e32 v207, 1.0, v207
	v_rcp_f32_e32 v180, v180
	v_rcp_f32_e32 v206, v206
	v_rcp_f32_e32 v207, v207
	v_cvt_pk_bf16_f32 v180, v180, v206
	v_cvt_pk_bf16_f32 v207, v207, v227
	ds_bpermute_b32 v206, v226, v180
	ds_bpermute_b32 v207, v226, v207
	v_add_f32_e32 v180, 1.0, v195
	v_add_f32_e32 v227, 1.0, v167
	v_rcp_f32_e32 v180, v180
	v_rcp_f32_e32 v227, v227
	s_waitcnt lgkmcnt(0)
	global_store_dwordx2 v[208:209], v[206:207], off offset:32
	v_add_f32_e32 v206, 1.0, v194
	v_add_f32_e32 v207, 1.0, v193
	v_rcp_f32_e32 v206, v206
	v_rcp_f32_e32 v207, v207
	v_cvt_pk_bf16_f32 v180, v180, v206
	v_cvt_pk_bf16_f32 v207, v207, v227
	ds_bpermute_b32 v206, v226, v180
	ds_bpermute_b32 v207, v226, v207
	v_add_f32_e32 v180, 1.0, v166
	v_add_f32_e32 v227, 1.0, v163
	v_rcp_f32_e32 v180, v180
	v_rcp_f32_e32 v227, v227
	s_waitcnt lgkmcnt(0)
	global_store_dwordx2 v[208:209], v[206:207], off offset:256
	v_add_f32_e32 v206, 1.0, v165
	v_add_f32_e32 v207, 1.0, v164
	v_rcp_f32_e32 v206, v206
	v_rcp_f32_e32 v207, v207
	v_cvt_pk_bf16_f32 v180, v180, v206
	v_cvt_pk_bf16_f32 v207, v207, v227
	ds_bpermute_b32 v206, v226, v180
	ds_bpermute_b32 v207, v226, v207
	v_mul_f32_e32 v180, 0xbfb8aa3b, v92
	v_exp_f32_e32 v180, v180
	v_mul_f32_e32 v227, 0xbfb8aa3b, v87
	v_exp_f32_e32 v227, v227
	s_waitcnt lgkmcnt(0)
	global_store_dwordx2 v[208:209], v[206:207], off offset:288
	v_mul_f32_e32 v206, 0xbfb8aa3b, v93
	v_mul_f32_e32 v207, 0xbfb8aa3b, v94
	v_mul_f32_e32 v208, 0xbfb8aa3b, v95
	v_exp_f32_e32 v206, v206
	v_exp_f32_e32 v207, v207
	v_exp_f32_e32 v208, v208
	v_add_f32_e32 v180, 1.0, v180
	v_add_f32_e32 v206, 1.0, v206
	v_add_f32_e32 v207, 1.0, v207
	v_add_f32_e32 v208, 1.0, v208
	v_rcp_f32_e32 v180, v180
	v_rcp_f32_e32 v206, v206
	v_rcp_f32_e32 v207, v207
	v_rcp_f32_e32 v208, v208
	v_add_f32_e32 v227, 1.0, v227
	v_cvt_pk_bf16_f32 v180, v180, v206
	ds_bpermute_b32 v206, v226, v180
	v_cvt_pk_bf16_f32 v207, v207, v208
	ds_bpermute_b32 v207, v226, v207
	v_lshl_add_u64 v[208:209], v[130:131], 0, s[4:5]
	s_mov_b32 s4, 0x20000
	v_add_co_u32_e32 v228, vcc, s4, v130
	v_mul_f32_e32 v180, 0xbfb8aa3b, v84
	s_nop 0
	v_addc_co_u32_e32 v229, vcc, 0, v131, vcc
	s_waitcnt lgkmcnt(0)
	global_store_dwordx2 v[228:229], v[206:207], off
	v_mul_f32_e32 v206, 0xbfb8aa3b, v85
	v_mul_f32_e32 v207, 0xbfb8aa3b, v86
	v_exp_f32_e32 v180, v180
	v_exp_f32_e32 v206, v206
	v_exp_f32_e32 v207, v207
	v_rcp_f32_e32 v227, v227
	v_add_f32_e32 v180, 1.0, v180
	v_add_f32_e32 v206, 1.0, v206
	v_add_f32_e32 v207, 1.0, v207
	v_rcp_f32_e32 v180, v180
	v_rcp_f32_e32 v206, v206
	v_rcp_f32_e32 v207, v207
	s_mov_b64 s[4:5], 0x30000
	v_cvt_pk_bf16_f32 v180, v180, v206
	v_cvt_pk_bf16_f32 v207, v207, v227
	ds_bpermute_b32 v206, v226, v180
	ds_bpermute_b32 v207, v226, v207
	v_add_f32_e32 v180, 1.0, v162
	v_add_f32_e32 v227, 1.0, v159
	v_rcp_f32_e32 v180, v180
	v_rcp_f32_e32 v227, v227
	s_waitcnt lgkmcnt(0)
	global_store_dwordx2 v[208:209], v[206:207], off offset:32
	v_add_f32_e32 v206, 1.0, v161
	v_add_f32_e32 v207, 1.0, v160
	v_rcp_f32_e32 v206, v206
	v_rcp_f32_e32 v207, v207
	v_cvt_pk_bf16_f32 v180, v180, v206
	v_cvt_pk_bf16_f32 v207, v207, v227
	ds_bpermute_b32 v206, v226, v180
	ds_bpermute_b32 v207, v226, v207
	v_add_f32_e32 v180, 1.0, v158
	v_add_f32_e32 v227, 1.0, v155
	v_rcp_f32_e32 v180, v180
	v_rcp_f32_e32 v227, v227
	s_waitcnt lgkmcnt(0)
	global_store_dwordx2 v[208:209], v[206:207], off offset:256
	v_add_f32_e32 v206, 1.0, v157
	v_add_f32_e32 v207, 1.0, v156
	v_rcp_f32_e32 v206, v206
	v_rcp_f32_e32 v207, v207
	v_cvt_pk_bf16_f32 v180, v180, v206
	v_cvt_pk_bf16_f32 v207, v207, v227
	ds_bpermute_b32 v206, v226, v180
	ds_bpermute_b32 v207, v226, v207
	v_mul_f32_e32 v180, 0xbfb8aa3b, v76
	v_exp_f32_e32 v180, v180
	v_mul_f32_e32 v227, 0xbfb8aa3b, v71
	v_exp_f32_e32 v227, v227
	s_waitcnt lgkmcnt(0)
	global_store_dwordx2 v[208:209], v[206:207], off offset:288
	v_mul_f32_e32 v206, 0xbfb8aa3b, v77
	v_mul_f32_e32 v207, 0xbfb8aa3b, v78
	v_mul_f32_e32 v208, 0xbfb8aa3b, v79
	v_exp_f32_e32 v206, v206
	v_exp_f32_e32 v207, v207
	v_exp_f32_e32 v208, v208
	v_add_f32_e32 v180, 1.0, v180
	v_add_f32_e32 v206, 1.0, v206
	v_add_f32_e32 v207, 1.0, v207
	v_add_f32_e32 v208, 1.0, v208
	v_rcp_f32_e32 v180, v180
	v_rcp_f32_e32 v206, v206
	v_rcp_f32_e32 v207, v207
	v_rcp_f32_e32 v208, v208
	v_add_f32_e32 v227, 1.0, v227
	v_cvt_pk_bf16_f32 v180, v180, v206
	ds_bpermute_b32 v206, v226, v180
	v_cvt_pk_bf16_f32 v207, v207, v208
	ds_bpermute_b32 v207, v226, v207
	v_lshl_add_u64 v[208:209], v[130:131], 0, s[4:5]
	s_mov_b32 s4, 0x30000
	v_add_co_u32_e32 v228, vcc, s4, v130
	v_mul_f32_e32 v180, 0xbfb8aa3b, v68
	s_nop 0
	v_addc_co_u32_e32 v229, vcc, 0, v131, vcc
	s_waitcnt lgkmcnt(0)
	global_store_dwordx2 v[228:229], v[206:207], off
	v_mul_f32_e32 v206, 0xbfb8aa3b, v69
	v_mul_f32_e32 v207, 0xbfb8aa3b, v70
	v_exp_f32_e32 v180, v180
	v_exp_f32_e32 v206, v206
	v_exp_f32_e32 v207, v207
	v_rcp_f32_e32 v227, v227
	v_add_f32_e32 v180, 1.0, v180
	v_add_f32_e32 v206, 1.0, v206
	v_add_f32_e32 v207, 1.0, v207
	v_rcp_f32_e32 v180, v180
	v_rcp_f32_e32 v206, v206
	v_rcp_f32_e32 v207, v207
	s_mov_b64 s[4:5], 0x80000
	v_cvt_pk_bf16_f32 v180, v180, v206
	v_cvt_pk_bf16_f32 v207, v207, v227
	ds_bpermute_b32 v206, v226, v180
	ds_bpermute_b32 v207, v226, v207
	v_add_f32_e32 v180, 1.0, v154
	v_add_f32_e32 v227, 1.0, v151
	v_rcp_f32_e32 v180, v180
	v_rcp_f32_e32 v227, v227
	s_waitcnt lgkmcnt(0)
	global_store_dwordx2 v[208:209], v[206:207], off offset:32
	v_add_f32_e32 v206, 1.0, v153
	v_add_f32_e32 v207, 1.0, v152
	v_rcp_f32_e32 v206, v206
	v_rcp_f32_e32 v207, v207
	v_cvt_pk_bf16_f32 v180, v180, v206
	v_cvt_pk_bf16_f32 v207, v207, v227
	ds_bpermute_b32 v206, v226, v180
	ds_bpermute_b32 v207, v226, v207
	v_add_f32_e32 v180, 1.0, v150
	v_add_f32_e32 v227, 1.0, v147
	v_rcp_f32_e32 v180, v180
	v_rcp_f32_e32 v227, v227
	s_waitcnt lgkmcnt(0)
	global_store_dwordx2 v[208:209], v[206:207], off offset:256
	v_add_f32_e32 v206, 1.0, v149
	v_add_f32_e32 v207, 1.0, v148
	v_rcp_f32_e32 v206, v206
	v_rcp_f32_e32 v207, v207
	v_cvt_pk_bf16_f32 v180, v180, v206
	v_cvt_pk_bf16_f32 v207, v207, v227
	ds_bpermute_b32 v206, v226, v180
	ds_bpermute_b32 v207, v226, v207
	v_mul_f32_e32 v180, 0xbfb8aa3b, v60
	v_exp_f32_e32 v180, v180
	v_mul_f32_e32 v227, 0xbfb8aa3b, v55
	v_exp_f32_e32 v227, v227
	s_waitcnt lgkmcnt(0)
	global_store_dwordx2 v[208:209], v[206:207], off offset:288
	v_mul_f32_e32 v206, 0xbfb8aa3b, v61
	v_mul_f32_e32 v207, 0xbfb8aa3b, v62
	v_mul_f32_e32 v208, 0xbfb8aa3b, v63
	v_exp_f32_e32 v206, v206
	v_exp_f32_e32 v207, v207
	v_exp_f32_e32 v208, v208
	v_add_f32_e32 v180, 1.0, v180
	v_add_f32_e32 v206, 1.0, v206
	v_add_f32_e32 v207, 1.0, v207
	v_add_f32_e32 v208, 1.0, v208
	v_rcp_f32_e32 v180, v180
	v_rcp_f32_e32 v206, v206
	v_rcp_f32_e32 v207, v207
	v_rcp_f32_e32 v208, v208
	v_add_f32_e32 v227, 1.0, v227
	v_cvt_pk_bf16_f32 v180, v180, v206
	ds_bpermute_b32 v206, v226, v180
	v_cvt_pk_bf16_f32 v207, v207, v208
	ds_bpermute_b32 v207, v226, v207
	v_lshl_add_u64 v[208:209], v[130:131], 0, s[4:5]
	s_mov_b32 s4, 0x80000
	v_add_co_u32_e32 v228, vcc, s4, v130
	v_mul_f32_e32 v180, 0xbfb8aa3b, v52
	s_nop 0
	v_addc_co_u32_e32 v229, vcc, 0, v131, vcc
	s_waitcnt lgkmcnt(0)
	global_store_dwordx2 v[228:229], v[206:207], off
	v_mul_f32_e32 v206, 0xbfb8aa3b, v53
	v_mul_f32_e32 v207, 0xbfb8aa3b, v54
	v_exp_f32_e32 v180, v180
	v_exp_f32_e32 v206, v206
	v_exp_f32_e32 v207, v207
	v_rcp_f32_e32 v227, v227
	v_add_f32_e32 v180, 1.0, v180
	v_add_f32_e32 v206, 1.0, v206
	v_add_f32_e32 v207, 1.0, v207
	v_rcp_f32_e32 v180, v180
	v_rcp_f32_e32 v206, v206
	v_rcp_f32_e32 v207, v207
	s_mov_b64 s[4:5], 0x90000
	v_cvt_pk_bf16_f32 v180, v180, v206
	v_cvt_pk_bf16_f32 v207, v207, v227
	ds_bpermute_b32 v206, v226, v180
	ds_bpermute_b32 v207, v226, v207
	v_exp_f32_e32 v180, v146
	v_exp_f32_e32 v227, v141
	s_waitcnt lgkmcnt(0)
	global_store_dwordx2 v[208:209], v[206:207], off offset:32
	v_exp_f32_e32 v206, v145
	v_exp_f32_e32 v207, v144
	v_add_f32_e32 v180, 1.0, v180
	v_add_f32_e32 v227, 1.0, v227
	v_add_f32_e32 v206, 1.0, v206
	v_add_f32_e32 v207, 1.0, v207
	v_rcp_f32_e32 v180, v180
	v_rcp_f32_e32 v206, v206
	v_rcp_f32_e32 v207, v207
	v_rcp_f32_e32 v227, v227
	v_cvt_pk_bf16_f32 v180, v180, v206
	ds_bpermute_b32 v206, v226, v180
	v_cvt_pk_bf16_f32 v207, v207, v227
	ds_bpermute_b32 v207, v226, v207
	v_exp_f32_e32 v180, v140
	v_exp_f32_e32 v227, v137
	s_waitcnt lgkmcnt(0)
	global_store_dwordx2 v[208:209], v[206:207], off offset:256
	v_exp_f32_e32 v206, v139
	v_exp_f32_e32 v207, v138
	v_add_f32_e32 v180, 1.0, v180
	v_add_f32_e32 v227, 1.0, v227
	v_add_f32_e32 v206, 1.0, v206
	v_add_f32_e32 v207, 1.0, v207
	v_rcp_f32_e32 v180, v180
	v_rcp_f32_e32 v206, v206
	v_rcp_f32_e32 v207, v207
	v_rcp_f32_e32 v227, v227
	v_cvt_pk_bf16_f32 v180, v180, v206
	ds_bpermute_b32 v206, v226, v180
	v_cvt_pk_bf16_f32 v207, v207, v227
	ds_bpermute_b32 v207, v226, v207
	v_mul_f32_e32 v180, 0xbfb8aa3b, v44
	v_exp_f32_e32 v180, v180
	v_mul_f32_e32 v227, 0xbfb8aa3b, v39
	v_exp_f32_e32 v227, v227
	s_waitcnt lgkmcnt(0)
	global_store_dwordx2 v[208:209], v[206:207], off offset:288
	v_mul_f32_e32 v206, 0xbfb8aa3b, v45
	v_mul_f32_e32 v207, 0xbfb8aa3b, v46
	v_mul_f32_e32 v208, 0xbfb8aa3b, v47
	v_exp_f32_e32 v206, v206
	v_exp_f32_e32 v207, v207
	v_exp_f32_e32 v208, v208
	v_add_f32_e32 v180, 1.0, v180
	v_add_f32_e32 v206, 1.0, v206
	v_add_f32_e32 v207, 1.0, v207
	v_add_f32_e32 v208, 1.0, v208
	v_rcp_f32_e32 v180, v180
	v_rcp_f32_e32 v206, v206
	v_rcp_f32_e32 v207, v207
	v_rcp_f32_e32 v208, v208
	v_add_f32_e32 v227, 1.0, v227
	v_cvt_pk_bf16_f32 v180, v180, v206
	ds_bpermute_b32 v206, v226, v180
	v_cvt_pk_bf16_f32 v207, v207, v208
	ds_bpermute_b32 v207, v226, v207
	v_lshl_add_u64 v[208:209], v[130:131], 0, s[4:5]
	s_mov_b32 s4, 0x90000
	v_add_co_u32_e32 v228, vcc, s4, v130
	v_mul_f32_e32 v180, 0xbfb8aa3b, v36
	s_nop 0
	v_addc_co_u32_e32 v229, vcc, 0, v131, vcc
	s_waitcnt lgkmcnt(0)
	global_store_dwordx2 v[228:229], v[206:207], off
	v_mul_f32_e32 v206, 0xbfb8aa3b, v37
	v_mul_f32_e32 v207, 0xbfb8aa3b, v38
	v_exp_f32_e32 v180, v180
	v_exp_f32_e32 v206, v206
	v_exp_f32_e32 v207, v207
	v_rcp_f32_e32 v227, v227
	v_add_f32_e32 v180, 1.0, v180
	v_add_f32_e32 v206, 1.0, v206
	v_add_f32_e32 v207, 1.0, v207
	v_rcp_f32_e32 v180, v180
	v_rcp_f32_e32 v206, v206
	v_rcp_f32_e32 v207, v207
	s_mov_b64 s[4:5], 0xa0000
	v_cvt_pk_bf16_f32 v180, v180, v206
	v_cvt_pk_bf16_f32 v207, v207, v227
	ds_bpermute_b32 v206, v226, v180
	ds_bpermute_b32 v207, v226, v207
	v_exp_f32_e32 v180, v136
	v_exp_f32_e32 v227, v132
	s_waitcnt lgkmcnt(0)
	global_store_dwordx2 v[208:209], v[206:207], off offset:32
	v_exp_f32_e32 v206, v135
	v_exp_f32_e32 v207, v134
	v_add_f32_e32 v180, 1.0, v180
	v_add_f32_e32 v227, 1.0, v227
	v_add_f32_e32 v206, 1.0, v206
	v_add_f32_e32 v207, 1.0, v207
	v_rcp_f32_e32 v180, v180
	v_rcp_f32_e32 v206, v206
	v_rcp_f32_e32 v207, v207
	v_rcp_f32_e32 v227, v227
	v_cvt_pk_bf16_f32 v180, v180, v206
	ds_bpermute_b32 v206, v226, v180
	v_cvt_pk_bf16_f32 v207, v207, v227
	ds_bpermute_b32 v207, v226, v207
	v_mul_f32_e32 v180, 0xbfb8aa3b, v32
	v_mul_f32_e32 v227, 0xbfb8aa3b, v35
	v_exp_f32_e32 v180, v180
	v_exp_f32_e32 v227, v227
	s_waitcnt lgkmcnt(0)
	global_store_dwordx2 v[208:209], v[206:207], off offset:256
	v_mul_f32_e32 v206, 0xbfb8aa3b, v33
	v_mul_f32_e32 v207, 0xbfb8aa3b, v34
	v_exp_f32_e32 v206, v206
	v_exp_f32_e32 v207, v207
	v_add_f32_e32 v180, 1.0, v180
	v_add_f32_e32 v227, 1.0, v227
	v_add_f32_e32 v206, 1.0, v206
	v_add_f32_e32 v207, 1.0, v207
	v_rcp_f32_e32 v180, v180
	v_rcp_f32_e32 v206, v206
	v_rcp_f32_e32 v207, v207
	v_rcp_f32_e32 v227, v227
	v_cvt_pk_bf16_f32 v180, v180, v206
	ds_bpermute_b32 v206, v226, v180
	v_cvt_pk_bf16_f32 v207, v207, v227
	ds_bpermute_b32 v207, v226, v207
	v_mul_f32_e32 v180, 0xbfb8aa3b, v28
	v_exp_f32_e32 v180, v180
	v_mul_f32_e32 v227, 0xbfb8aa3b, v23
	v_exp_f32_e32 v227, v227
	s_waitcnt lgkmcnt(0)
	global_store_dwordx2 v[208:209], v[206:207], off offset:288
	v_mul_f32_e32 v206, 0xbfb8aa3b, v29
	v_mul_f32_e32 v207, 0xbfb8aa3b, v30
	v_mul_f32_e32 v208, 0xbfb8aa3b, v31
	v_exp_f32_e32 v206, v206
	v_exp_f32_e32 v207, v207
	v_exp_f32_e32 v208, v208
	v_add_f32_e32 v180, 1.0, v180
	v_add_f32_e32 v206, 1.0, v206
	v_add_f32_e32 v207, 1.0, v207
	v_add_f32_e32 v208, 1.0, v208
	v_rcp_f32_e32 v180, v180
	v_rcp_f32_e32 v206, v206
	v_rcp_f32_e32 v207, v207
	v_rcp_f32_e32 v208, v208
	v_add_f32_e32 v227, 1.0, v227
	v_cvt_pk_bf16_f32 v180, v180, v206
	ds_bpermute_b32 v206, v226, v180
	v_cvt_pk_bf16_f32 v207, v207, v208
	ds_bpermute_b32 v207, v226, v207
	v_lshl_add_u64 v[208:209], v[130:131], 0, s[4:5]
	s_mov_b32 s4, 0xa0000
	v_add_co_u32_e32 v228, vcc, s4, v130
	v_mul_f32_e32 v180, 0xbfb8aa3b, v20
	s_nop 0
	v_addc_co_u32_e32 v229, vcc, 0, v131, vcc
	s_waitcnt lgkmcnt(0)
	global_store_dwordx2 v[228:229], v[206:207], off
	v_mul_f32_e32 v206, 0xbfb8aa3b, v21
	v_mul_f32_e32 v207, 0xbfb8aa3b, v22
	v_exp_f32_e32 v180, v180
	v_exp_f32_e32 v206, v206
	v_exp_f32_e32 v207, v207
	v_rcp_f32_e32 v227, v227
	v_add_f32_e32 v180, 1.0, v180
	v_add_f32_e32 v206, 1.0, v206
	v_add_f32_e32 v207, 1.0, v207
	v_rcp_f32_e32 v180, v180
	v_rcp_f32_e32 v206, v206
	v_rcp_f32_e32 v207, v207
	s_mov_b64 s[4:5], 0xb0000
	v_cvt_pk_bf16_f32 v180, v180, v206
	v_cvt_pk_bf16_f32 v207, v207, v227
	ds_bpermute_b32 v206, v226, v180
	ds_bpermute_b32 v207, v226, v207
	v_mul_f32_e32 v180, 0xbfb8aa3b, v24
	v_mul_f32_e32 v227, 0xbfb8aa3b, v27
	v_exp_f32_e32 v180, v180
	v_exp_f32_e32 v227, v227
	s_waitcnt lgkmcnt(0)
	global_store_dwordx2 v[208:209], v[206:207], off offset:32
	v_mul_f32_e32 v206, 0xbfb8aa3b, v25
	v_mul_f32_e32 v207, 0xbfb8aa3b, v26
	v_exp_f32_e32 v206, v206
	v_exp_f32_e32 v207, v207
	v_add_f32_e32 v180, 1.0, v180
	v_add_f32_e32 v227, 1.0, v227
	v_add_f32_e32 v206, 1.0, v206
	v_add_f32_e32 v207, 1.0, v207
	v_rcp_f32_e32 v180, v180
	v_rcp_f32_e32 v206, v206
	v_rcp_f32_e32 v207, v207
	v_rcp_f32_e32 v227, v227
	v_cvt_pk_bf16_f32 v180, v180, v206
	ds_bpermute_b32 v206, v226, v180
	v_cvt_pk_bf16_f32 v207, v207, v227
	ds_bpermute_b32 v207, v226, v207
	v_mul_f32_e32 v180, 0xbfb8aa3b, v16
	v_mul_f32_e32 v227, 0xbfb8aa3b, v19
	v_exp_f32_e32 v180, v180
	v_exp_f32_e32 v227, v227
	s_waitcnt lgkmcnt(0)
	global_store_dwordx2 v[208:209], v[206:207], off offset:256
	v_mul_f32_e32 v206, 0xbfb8aa3b, v17
	v_mul_f32_e32 v207, 0xbfb8aa3b, v18
	v_exp_f32_e32 v206, v206
	v_exp_f32_e32 v207, v207
	v_add_f32_e32 v180, 1.0, v180
	v_add_f32_e32 v227, 1.0, v227
	v_add_f32_e32 v206, 1.0, v206
	v_add_f32_e32 v207, 1.0, v207
	v_rcp_f32_e32 v180, v180
	v_rcp_f32_e32 v206, v206
	v_rcp_f32_e32 v207, v207
	v_rcp_f32_e32 v227, v227
	v_cvt_pk_bf16_f32 v180, v180, v206
	ds_bpermute_b32 v206, v226, v180
	v_cvt_pk_bf16_f32 v207, v207, v227
	ds_bpermute_b32 v207, v226, v207
	v_mul_f32_e32 v180, 0xbfb8aa3b, v12
	v_exp_f32_e32 v180, v180
	s_waitcnt lgkmcnt(0)
	global_store_dwordx2 v[208:209], v[206:207], off offset:288
	v_mul_f32_e32 v206, 0xbfb8aa3b, v13
	v_mul_f32_e32 v207, 0xbfb8aa3b, v14
	v_mul_f32_e32 v208, 0xbfb8aa3b, v15
	v_exp_f32_e32 v206, v206
	v_exp_f32_e32 v207, v207
	v_exp_f32_e32 v208, v208
	v_add_f32_e32 v180, 1.0, v180
	v_add_f32_e32 v206, 1.0, v206
	v_add_f32_e32 v207, 1.0, v207
	v_add_f32_e32 v208, 1.0, v208
	v_rcp_f32_e32 v180, v180
	v_rcp_f32_e32 v206, v206
	v_rcp_f32_e32 v207, v207
	v_rcp_f32_e32 v208, v208
	v_cvt_pk_bf16_f32 v180, v180, v206
	ds_bpermute_b32 v206, v226, v180
	v_cvt_pk_bf16_f32 v207, v207, v208
	ds_bpermute_b32 v207, v226, v207
	v_lshl_add_u64 v[208:209], v[130:131], 0, s[4:5]
	s_mov_b32 s4, 0xb0000
	v_add_co_u32_e32 v130, vcc, s4, v130
	v_mul_f32_e32 v180, 0xbfb8aa3b, v6
	s_nop 0
	v_addc_co_u32_e32 v131, vcc, 0, v131, vcc
	s_waitcnt lgkmcnt(0)
	global_store_dwordx2 v[130:131], v[206:207], off
	v_mul_f32_e32 v130, 0xbfb8aa3b, v4
	v_mul_f32_e32 v131, 0xbfb8aa3b, v5
	v_mul_f32_e32 v206, 0xbfb8aa3b, v7
	v_exp_f32_e32 v130, v130
	v_exp_f32_e32 v131, v131
	v_exp_f32_e32 v180, v180
	v_exp_f32_e32 v206, v206
	v_add_f32_e32 v130, 1.0, v130
	v_add_f32_e32 v131, 1.0, v131
	v_add_f32_e32 v180, 1.0, v180
	v_add_f32_e32 v206, 1.0, v206
	v_rcp_f32_e32 v130, v130
	v_rcp_f32_e32 v131, v131
	v_rcp_f32_e32 v180, v180
	v_rcp_f32_e32 v206, v206
	s_mov_b64 s[4:5], 0
	v_cvt_pk_bf16_f32 v130, v130, v131
	ds_bpermute_b32 v130, v226, v130
	v_cvt_pk_bf16_f32 v131, v180, v206
	ds_bpermute_b32 v131, v226, v131
	v_mul_f32_e32 v180, 0xbfb8aa3b, v10
	v_mul_f32_e32 v206, 0xbfb8aa3b, v11
	v_exp_f32_e32 v180, v180
	v_exp_f32_e32 v206, v206
	s_waitcnt lgkmcnt(0)
	global_store_dwordx2 v[208:209], v[130:131], off offset:32
	v_mul_f32_e32 v130, 0xbfb8aa3b, v8
	v_mul_f32_e32 v131, 0xbfb8aa3b, v9
	v_exp_f32_e32 v130, v130
	v_exp_f32_e32 v131, v131
	v_add_f32_e32 v180, 1.0, v180
	v_add_f32_e32 v206, 1.0, v206
	v_add_f32_e32 v130, 1.0, v130
	v_add_f32_e32 v131, 1.0, v131
	v_rcp_f32_e32 v130, v130
	v_rcp_f32_e32 v131, v131
	v_rcp_f32_e32 v180, v180
	v_rcp_f32_e32 v206, v206
	v_cvt_pk_bf16_f32 v130, v130, v131
	ds_bpermute_b32 v130, v226, v130
	v_cvt_pk_bf16_f32 v131, v180, v206
	ds_bpermute_b32 v131, v226, v131
	v_mul_f32_e32 v180, 0xbfb8aa3b, v2
	v_mul_f32_e32 v206, 0xbfb8aa3b, v3
	v_exp_f32_e32 v180, v180
	v_exp_f32_e32 v206, v206
	s_waitcnt lgkmcnt(0)
	global_store_dwordx2 v[208:209], v[130:131], off offset:256
	v_mul_f32_e32 v130, 0xbfb8aa3b, v0
	v_mul_f32_e32 v131, 0xbfb8aa3b, v1
	v_exp_f32_e32 v130, v130
	v_exp_f32_e32 v131, v131
	v_add_f32_e32 v180, 1.0, v180
	v_add_f32_e32 v206, 1.0, v206
	v_add_f32_e32 v130, 1.0, v130
	v_add_f32_e32 v131, 1.0, v131
	v_rcp_f32_e32 v130, v130
	v_rcp_f32_e32 v131, v131
	v_rcp_f32_e32 v180, v180
	v_rcp_f32_e32 v206, v206
	v_cvt_pk_bf16_f32 v130, v130, v131
	ds_bpermute_b32 v130, v226, v130
	v_cvt_pk_bf16_f32 v131, v180, v206
	ds_bpermute_b32 v131, v226, v131
	s_waitcnt lgkmcnt(0)
	global_store_dwordx2 v[208:209], v[130:131], off offset:288

.LBB0_1024:
	s_waitcnt lgkmcnt(0)
	ds_read_b128 v[128:131], v179
	ds_read_b128 v[132:135], v179 offset:1024
	ds_read_b128 v[136:139], v179 offset:2048
	ds_read_b128 v[140:143], v179 offset:3072
	s_add_i32 s62, s36, 2
	s_add_u32 s37, s4, 0xfff80080
	s_addc_u32 s38, s5, -1
	s_cmp_eq_u32 s59, s36
	s_cselect_b32 s36, s58, s60
	s_cselect_b32 s39, s21, s38
	s_cselect_b32 s38, s25, s37
	s_cselect_b32 s37, s23, s61
	v_lshl_add_u64 v[166:167], s[4:5], 0, v[162:163]
	s_add_i32 m0, s31, 0xc000
	ds_read_b128 v[144:147], v190
	ds_read_b128 v[148:151], v190 offset:1024
	ds_read_b128 v[152:155], v190 offset:2048
	ds_read_b128 v[156:159], v190 offset:3072
	ds_read_b128 v[180:183], v190 offset:4096
	ds_read_b128 v[184:187], v190 offset:5120
	ds_read_b128 v[194:197], v190 offset:6144
	ds_read_b128 v[198:201], v190 offset:7168
	global_load_lds_dwordx4 v[166:167], off
	v_lshl_add_u64 v[166:167], s[4:5], 0, v[164:165]
	s_add_i32 m0, s31, 0xe000
	s_nop 0
	global_load_lds_dwordx4 v[166:167], off
	s_waitcnt lgkmcnt(8)
	s_barrier
	s_waitcnt lgkmcnt(0)

	s_waitcnt lgkmcnt(0)
	v_mfma_f32_16x16x32_bf16 v[124:127], v[128:131], v[144:147], v[124:127]
	v_mfma_f32_16x16x32_bf16 v[120:123], v[136:139], v[144:147], v[120:123]
	v_mfma_f32_16x16x32_bf16 v[116:119], v[128:131], v[152:155], v[116:119]
	v_mfma_f32_16x16x32_bf16 v[104:107], v[136:139], v[152:155], v[104:107]
	v_mfma_f32_16x16x32_bf16 v[96:99], v[128:131], v[180:183], v[96:99]
	v_mfma_f32_16x16x32_bf16 v[88:91], v[136:139], v[180:183], v[88:91]
	v_mfma_f32_16x16x32_bf16 v[80:83], v[128:131], v[194:197], v[80:83]
	v_mfma_f32_16x16x32_bf16 v[72:75], v[136:139], v[194:197], v[72:75]
	v_mfma_f32_16x16x32_bf16 v[124:127], v[132:135], v[148:151], v[124:127]
	v_mfma_f32_16x16x32_bf16 v[120:123], v[140:143], v[148:151], v[120:123]
	v_mfma_f32_16x16x32_bf16 v[116:119], v[132:135], v[156:159], v[116:119]
	v_mfma_f32_16x16x32_bf16 v[104:107], v[140:143], v[156:159], v[104:107]
	v_mfma_f32_16x16x32_bf16 v[96:99], v[132:135], v[184:187], v[96:99]
	v_mfma_f32_16x16x32_bf16 v[88:91], v[140:143], v[184:187], v[88:91]
	v_mfma_f32_16x16x32_bf16 v[80:83], v[132:135], v[198:201], v[80:83]
	v_mfma_f32_16x16x32_bf16 v[72:75], v[140:143], v[198:201], v[72:75]

	s_barrier
	s_add_i32 s63, s52, s42
	v_lshl_add_u64 v[166:167], s[36:37], 0, v[172:173]
	s_mov_b32 m0, s63
	ds_read_b128 v[202:205], v191
	ds_read_b128 v[206:209], v191 offset:1024
	ds_read_b128 v[222:225], v191 offset:2048
	ds_read_b128 v[226:229], v191 offset:3072
	global_load_lds_dwordx4 v[166:167], off
	v_lshl_add_u64 v[188:189], s[36:37], 0, v[174:175]
	s_add_i32 m0, s63, 0x2000
	s_nop 0
	global_load_lds_dwordx4 v[188:189], off
	s_barrier
	s_waitcnt lgkmcnt(0)

	s_waitcnt lgkmcnt(0)
	v_mfma_f32_16x16x32_bf16 v[112:115], v[202:205], v[144:147], v[112:115]
	v_mfma_f32_16x16x32_bf16 v[108:111], v[222:225], v[144:147], v[108:111]
	v_mfma_f32_16x16x32_bf16 v[100:103], v[202:205], v[152:155], v[100:103]
	v_mfma_f32_16x16x32_bf16 v[92:95], v[222:225], v[152:155], v[92:95]
	v_mfma_f32_16x16x32_bf16 v[84:87], v[202:205], v[180:183], v[84:87]
	v_mfma_f32_16x16x32_bf16 v[76:79], v[222:225], v[180:183], v[76:79]
	v_mfma_f32_16x16x32_bf16 v[68:71], v[202:205], v[194:197], v[68:71]
	v_mfma_f32_16x16x32_bf16 v[64:67], v[222:225], v[194:197], v[64:67]
	v_mfma_f32_16x16x32_bf16 v[112:115], v[206:209], v[148:151], v[112:115]
	v_mfma_f32_16x16x32_bf16 v[108:111], v[226:229], v[148:151], v[108:111]
	v_mfma_f32_16x16x32_bf16 v[100:103], v[206:209], v[156:159], v[100:103]
	v_mfma_f32_16x16x32_bf16 v[92:95], v[226:229], v[156:159], v[92:95]
	v_mfma_f32_16x16x32_bf16 v[84:87], v[206:209], v[184:187], v[84:87]
	v_mfma_f32_16x16x32_bf16 v[76:79], v[226:229], v[184:187], v[76:79]
	v_mfma_f32_16x16x32_bf16 v[68:71], v[206:209], v[198:201], v[68:71]
	v_mfma_f32_16x16x32_bf16 v[64:67], v[226:229], v[198:201], v[64:67]

	s_mov_b32 m0, s31
	v_lshl_add_u64 v[230:231], s[38:39], 0, v[172:173]
	s_barrier
	ds_read_b128 v[144:147], v190 offset:16384
	ds_read_b128 v[148:151], v190 offset:17408
	ds_read_b128 v[152:155], v190 offset:18432
	ds_read_b128 v[156:159], v190 offset:19456
	ds_read_b128 v[180:183], v190 offset:20480
	ds_read_b128 v[184:187], v190 offset:21504
	ds_read_b128 v[194:197], v190 offset:22528
	ds_read_b128 v[198:201], v190 offset:23552
	global_load_lds_dwordx4 v[230:231], off
	v_lshl_add_u64 v[232:233], s[38:39], 0, v[174:175]
	s_mov_b32 m0, s35
	s_nop 0
	global_load_lds_dwordx4 v[232:233], off
	s_barrier
	s_waitcnt lgkmcnt(0)

	s_waitcnt lgkmcnt(0)
	v_mfma_f32_16x16x32_bf16 v[60:63], v[128:131], v[144:147], v[60:63]
	v_mfma_f32_16x16x32_bf16 v[56:59], v[136:139], v[144:147], v[56:59]
	v_mfma_f32_16x16x32_bf16 v[52:55], v[128:131], v[152:155], v[52:55]
	v_mfma_f32_16x16x32_bf16 v[40:43], v[136:139], v[152:155], v[40:43]
	v_mfma_f32_16x16x32_bf16 v[36:39], v[128:131], v[180:183], v[36:39]
	v_mfma_f32_16x16x32_bf16 v[24:27], v[136:139], v[180:183], v[24:27]
	v_mfma_f32_16x16x32_bf16 v[20:23], v[128:131], v[194:197], v[20:23]
	v_mfma_f32_16x16x32_bf16 v[8:11], v[136:139], v[194:197], v[8:11]
	v_mfma_f32_16x16x32_bf16 v[60:63], v[132:135], v[148:151], v[60:63]
	v_mfma_f32_16x16x32_bf16 v[56:59], v[140:143], v[148:151], v[56:59]
	v_mfma_f32_16x16x32_bf16 v[52:55], v[132:135], v[156:159], v[52:55]
	v_mfma_f32_16x16x32_bf16 v[40:43], v[140:143], v[156:159], v[40:43]
	v_mfma_f32_16x16x32_bf16 v[36:39], v[132:135], v[184:187], v[36:39]
	v_mfma_f32_16x16x32_bf16 v[24:27], v[140:143], v[184:187], v[24:27]
	v_mfma_f32_16x16x32_bf16 v[20:23], v[132:135], v[198:201], v[20:23]
	v_mfma_f32_16x16x32_bf16 v[8:11], v[140:143], v[198:201], v[8:11]

	s_barrier
	s_add_u32 s64, s36, 0x80000
	s_addc_u32 s65, s37, 0
	s_add_i32 s63, s53, s42
	v_lshl_add_u64 v[128:129], s[64:65], 0, v[172:173]
	s_mov_b32 m0, s63
	s_nop 0
	global_load_lds_dwordx4 v[128:129], off
	v_lshl_add_u64 v[128:129], s[64:65], 0, v[174:175]
	s_add_i32 m0, s63, 0x2000
	s_nop 0
	global_load_lds_dwordx4 v[128:129], off
	s_waitcnt vmcnt(6)
	s_barrier

	v_mfma_f32_16x16x32_bf16 v[48:51], v[202:205], v[144:147], v[48:51]
	v_mfma_f32_16x16x32_bf16 v[44:47], v[222:225], v[144:147], v[44:47]
	v_mfma_f32_16x16x32_bf16 v[32:35], v[202:205], v[152:155], v[32:35]
	v_mfma_f32_16x16x32_bf16 v[28:31], v[222:225], v[152:155], v[28:31]
	v_mfma_f32_16x16x32_bf16 v[16:19], v[202:205], v[180:183], v[16:19]
	v_mfma_f32_16x16x32_bf16 v[12:15], v[222:225], v[180:183], v[12:15]
	v_mfma_f32_16x16x32_bf16 v[4:7], v[202:205], v[194:197], v[4:7]
	v_mfma_f32_16x16x32_bf16 v[0:3], v[222:225], v[194:197], v[0:3]
	v_mfma_f32_16x16x32_bf16 v[48:51], v[206:209], v[148:151], v[48:51]
	v_mfma_f32_16x16x32_bf16 v[44:47], v[226:229], v[148:151], v[44:47]
	v_mfma_f32_16x16x32_bf16 v[32:35], v[206:209], v[156:159], v[32:35]
	v_mfma_f32_16x16x32_bf16 v[28:31], v[226:229], v[156:159], v[28:31]
	v_mfma_f32_16x16x32_bf16 v[16:19], v[206:209], v[184:187], v[16:19]
	v_mfma_f32_16x16x32_bf16 v[12:15], v[226:229], v[184:187], v[12:15]
	v_mfma_f32_16x16x32_bf16 v[4:7], v[206:209], v[198:201], v[4:7]
	v_mfma_f32_16x16x32_bf16 v[0:3], v[226:229], v[198:201], v[0:3]

	s_add_i32 s63, 0, 0x18000
	v_add_u32_e32 v140, s63, v177
	s_barrier
	ds_read_b128 v[128:131], v140
	ds_read_b128 v[132:135], v140 offset:1024
	ds_read_b128 v[136:139], v140 offset:2048
	ds_read_b128 v[140:143], v140 offset:3072
	s_add_u32 s38, s38, 0x80000
	s_addc_u32 s39, s39, 0
	s_mov_b32 m0, s43
	v_lshl_add_u64 v[202:203], s[38:39], 0, v[172:173]
	ds_read_b128 v[144:147], v190 offset:32768
	ds_read_b128 v[148:151], v190 offset:33792
	ds_read_b128 v[152:155], v190 offset:34816
	ds_read_b128 v[156:159], v190 offset:35840
	ds_read_b128 v[180:183], v190 offset:36864
	ds_read_b128 v[184:187], v190 offset:37888
	ds_read_b128 v[194:197], v190 offset:38912
	ds_read_b128 v[198:201], v190 offset:39936
	global_load_lds_dwordx4 v[202:203], off
	v_lshl_add_u64 v[202:203], s[38:39], 0, v[174:175]
	s_mov_b32 m0, s44
	s_nop 0
	global_load_lds_dwordx4 v[202:203], off
	s_waitcnt lgkmcnt(8)
	s_barrier
	s_waitcnt lgkmcnt(0)

	s_waitcnt lgkmcnt(0)
	v_mfma_f32_16x16x32_bf16 v[124:127], v[128:131], v[144:147], v[124:127]
	v_mfma_f32_16x16x32_bf16 v[120:123], v[136:139], v[144:147], v[120:123]
	v_mfma_f32_16x16x32_bf16 v[116:119], v[128:131], v[152:155], v[116:119]
	v_mfma_f32_16x16x32_bf16 v[104:107], v[136:139], v[152:155], v[104:107]
	v_mfma_f32_16x16x32_bf16 v[96:99], v[128:131], v[180:183], v[96:99]
	v_mfma_f32_16x16x32_bf16 v[88:91], v[136:139], v[180:183], v[88:91]
	v_mfma_f32_16x16x32_bf16 v[80:83], v[128:131], v[194:197], v[80:83]
	v_mfma_f32_16x16x32_bf16 v[72:75], v[136:139], v[194:197], v[72:75]
	v_mfma_f32_16x16x32_bf16 v[124:127], v[132:135], v[148:151], v[124:127]
	v_mfma_f32_16x16x32_bf16 v[120:123], v[140:143], v[148:151], v[120:123]
	v_mfma_f32_16x16x32_bf16 v[116:119], v[132:135], v[156:159], v[116:119]
	v_mfma_f32_16x16x32_bf16 v[104:107], v[140:143], v[156:159], v[104:107]
	v_mfma_f32_16x16x32_bf16 v[96:99], v[132:135], v[184:187], v[96:99]
	v_mfma_f32_16x16x32_bf16 v[88:91], v[140:143], v[184:187], v[88:91]
	v_mfma_f32_16x16x32_bf16 v[80:83], v[132:135], v[198:201], v[80:83]
	v_mfma_f32_16x16x32_bf16 v[72:75], v[140:143], v[198:201], v[72:75]

	s_barrier
	s_add_i32 s38, 0, 0x1c000
	s_add_i32 s39, s63, s42
	v_add_u32_e32 v160, s38, v177
	v_lshl_add_u64 v[166:167], v[166:167], 0, s[14:15]
	s_mov_b32 m0, s39
	ds_read_b128 v[202:205], v160
	ds_read_b128 v[206:209], v160 offset:1024
	ds_read_b128 v[222:225], v160 offset:2048
	ds_read_b128 v[226:229], v160 offset:3072
	global_load_lds_dwordx4 v[166:167], off
	v_lshl_add_u64 v[166:167], v[188:189], 0, s[14:15]
	s_add_i32 m0, s39, 0x2000
	s_nop 0
	global_load_lds_dwordx4 v[166:167], off
	s_barrier
	s_waitcnt lgkmcnt(0)

	s_waitcnt lgkmcnt(0)
	v_mfma_f32_16x16x32_bf16 v[112:115], v[202:205], v[144:147], v[112:115]
	v_mfma_f32_16x16x32_bf16 v[108:111], v[222:225], v[144:147], v[108:111]
	v_mfma_f32_16x16x32_bf16 v[100:103], v[202:205], v[152:155], v[100:103]
	v_mfma_f32_16x16x32_bf16 v[92:95], v[222:225], v[152:155], v[92:95]
	v_mfma_f32_16x16x32_bf16 v[84:87], v[202:205], v[180:183], v[84:87]
	v_mfma_f32_16x16x32_bf16 v[76:79], v[222:225], v[180:183], v[76:79]
	v_mfma_f32_16x16x32_bf16 v[68:71], v[202:205], v[194:197], v[68:71]
	v_mfma_f32_16x16x32_bf16 v[64:67], v[222:225], v[194:197], v[64:67]
	v_mfma_f32_16x16x32_bf16 v[112:115], v[206:209], v[148:151], v[112:115]
	v_mfma_f32_16x16x32_bf16 v[108:111], v[226:229], v[148:151], v[108:111]
	v_mfma_f32_16x16x32_bf16 v[100:103], v[206:209], v[156:159], v[100:103]
	v_mfma_f32_16x16x32_bf16 v[92:95], v[226:229], v[156:159], v[92:95]
	v_mfma_f32_16x16x32_bf16 v[84:87], v[206:209], v[184:187], v[84:87]
	v_mfma_f32_16x16x32_bf16 v[76:79], v[226:229], v[184:187], v[76:79]
	v_mfma_f32_16x16x32_bf16 v[68:71], v[206:209], v[198:201], v[68:71]
	v_mfma_f32_16x16x32_bf16 v[64:67], v[226:229], v[198:201], v[64:67]

	s_mov_b32 m0, s48
	v_lshl_add_u64 v[166:167], v[230:231], 0, s[14:15]
	s_barrier
	ds_read_b128 v[144:147], v190 offset:49152
	ds_read_b128 v[148:151], v190 offset:50176
	ds_read_b128 v[152:155], v190 offset:51200
	ds_read_b128 v[156:159], v190 offset:52224
	ds_read_b128 v[180:183], v190 offset:53248
	ds_read_b128 v[184:187], v190 offset:54272
	ds_read_b128 v[194:197], v190 offset:55296
	ds_read_b128 v[198:201], v190 offset:56320
	global_load_lds_dwordx4 v[166:167], off
	v_lshl_add_u64 v[166:167], v[232:233], 0, s[14:15]
	s_mov_b32 m0, s49
	s_nop 0
	global_load_lds_dwordx4 v[166:167], off
	s_barrier
	s_waitcnt lgkmcnt(0)

	s_waitcnt lgkmcnt(0)
	v_mfma_f32_16x16x32_bf16 v[60:63], v[128:131], v[144:147], v[60:63]
	v_mfma_f32_16x16x32_bf16 v[56:59], v[136:139], v[144:147], v[56:59]
	v_mfma_f32_16x16x32_bf16 v[52:55], v[128:131], v[152:155], v[52:55]
	v_mfma_f32_16x16x32_bf16 v[40:43], v[136:139], v[152:155], v[40:43]
	v_mfma_f32_16x16x32_bf16 v[36:39], v[128:131], v[180:183], v[36:39]
	v_mfma_f32_16x16x32_bf16 v[24:27], v[136:139], v[180:183], v[24:27]
	v_mfma_f32_16x16x32_bf16 v[20:23], v[128:131], v[194:197], v[20:23]
	v_mfma_f32_16x16x32_bf16 v[8:11], v[136:139], v[194:197], v[8:11]
	v_mfma_f32_16x16x32_bf16 v[60:63], v[132:135], v[148:151], v[60:63]
	v_mfma_f32_16x16x32_bf16 v[56:59], v[140:143], v[148:151], v[56:59]
	v_mfma_f32_16x16x32_bf16 v[52:55], v[132:135], v[156:159], v[52:55]
	v_mfma_f32_16x16x32_bf16 v[40:43], v[140:143], v[156:159], v[40:43]
	v_mfma_f32_16x16x32_bf16 v[36:39], v[132:135], v[184:187], v[36:39]
	v_mfma_f32_16x16x32_bf16 v[24:27], v[140:143], v[184:187], v[24:27]
	v_mfma_f32_16x16x32_bf16 v[20:23], v[132:135], v[198:201], v[20:23]
	v_mfma_f32_16x16x32_bf16 v[8:11], v[140:143], v[198:201], v[8:11]

	s_barrier
	s_add_u32 s36, s36, 0x80080
	s_addc_u32 s37, s37, 0
	s_add_i32 s38, s38, s42
	v_lshl_add_u64 v[128:129], s[36:37], 0, v[172:173]
	s_mov_b32 m0, s38
	s_nop 0
	global_load_lds_dwordx4 v[128:129], off
	v_lshl_add_u64 v[128:129], s[36:37], 0, v[174:175]
	s_add_i32 m0, s38, 0x2000
	s_nop 0
	global_load_lds_dwordx4 v[128:129], off
	s_waitcnt vmcnt(6)
	s_barrier

	v_mfma_f32_16x16x32_bf16 v[48:51], v[202:205], v[144:147], v[48:51]
	v_mfma_f32_16x16x32_bf16 v[44:47], v[222:225], v[144:147], v[44:47]
	v_mfma_f32_16x16x32_bf16 v[32:35], v[202:205], v[152:155], v[32:35]
	v_mfma_f32_16x16x32_bf16 v[28:31], v[222:225], v[152:155], v[28:31]
	v_mfma_f32_16x16x32_bf16 v[16:19], v[202:205], v[180:183], v[16:19]
	v_mfma_f32_16x16x32_bf16 v[12:15], v[222:225], v[180:183], v[12:15]
	v_mfma_f32_16x16x32_bf16 v[4:7], v[202:205], v[194:197], v[4:7]
	v_mfma_f32_16x16x32_bf16 v[0:3], v[222:225], v[194:197], v[0:3]
	v_mfma_f32_16x16x32_bf16 v[48:51], v[206:209], v[148:151], v[48:51]
	v_mfma_f32_16x16x32_bf16 v[44:47], v[226:229], v[148:151], v[44:47]
	v_mfma_f32_16x16x32_bf16 v[32:35], v[206:209], v[156:159], v[32:35]
	v_mfma_f32_16x16x32_bf16 v[28:31], v[226:229], v[156:159], v[28:31]
	v_mfma_f32_16x16x32_bf16 v[16:19], v[206:209], v[184:187], v[16:19]
	v_mfma_f32_16x16x32_bf16 v[12:15], v[226:229], v[184:187], v[12:15]
	v_mfma_f32_16x16x32_bf16 v[4:7], v[206:209], v[198:201], v[4:7]
	v_mfma_f32_16x16x32_bf16 v[0:3], v[226:229], v[198:201], v[0:3]

	s_add_u32 s4, s4, 0x100
	s_addc_u32 s5, s5, 0
	s_add_u32 s60, s60, 0x100
	s_addc_u32 s61, s61, 0
	s_cmp_ge_i32 s62, s17
	s_mov_b32 s36, s62
	s_barrier
	s_cbranch_scc0 .LBB0_1024
	v_mov_b32_e32 v128, v210
	v_mov_b32_e32 v129, v169
	s_cmp_lt_i32 s12, 0
	v_lshl_add_u32 v128, v128, 4, v129
	v_ashrrev_i32_e32 v166, 2, v128
	v_and_b32_e32 v160, 3, v129
	v_and_b32_e32 v128, -4, v128
	v_lshl_add_u32 v193, v160, 6, v128
	s_mov_b64 s[4:5], -1
	s_cbranch_scc0 .LBB0_1043
	s_lshl_b32 s4, s30, 8
	v_lshl_or_b32 v128, v160, 2, s4
	s_lshl_b32 s4, s34, 8
	v_or_b32_e32 v180, s47, v128
	s_add_i32 s4, s4, s46
	v_readlane_b32 s60, v254, 6
	v_ashrrev_i32_e32 v181, 31, v180
	v_add_u32_e32 v184, s4, v166
	s_cmp_lt_i32 s34, 32
	v_readlane_b32 s61, v254, 7
	v_lshlrev_b64 v[128:129], 2, v[180:181]
	v_readlane_b32 s62, v254, 8
	v_readlane_b32 s63, v254, 9
	v_readlane_b32 s64, v254, 10
	v_readlane_b32 s65, v254, 11
	v_readlane_b32 s66, v254, 12
	v_readlane_b32 s67, v254, 13
	v_readlane_b32 s68, v254, 14
	v_readlane_b32 s69, v254, 15
	v_readlane_b32 s70, v254, 16
	v_readlane_b32 s71, v254, 17
	v_readlane_b32 s72, v254, 18
	v_readlane_b32 s73, v254, 19
	v_readlane_b32 s74, v254, 20
	v_readlane_b32 s75, v254, 21
	s_cselect_b32 s5, s61, s51
	s_cselect_b32 s4, s60, s50
	v_ashrrev_i32_e32 v185, 31, v184
	v_lshl_add_u64 v[182:183], s[4:5], 0, v[128:129]
	v_lshlrev_b64 v[130:131], 13, v[184:185]
	v_readlane_b32 s60, v254, 22
	v_lshl_add_u64 v[136:137], v[182:183], 0, v[130:131]
	v_readlane_b32 s61, v254, 23
	v_readlane_b32 s68, v254, 30
	v_readlane_b32 s69, v254, 31
	global_load_dwordx4 v[196:199], v[136:137], off nt
	global_load_dwordx4 v[200:203], v[136:137], off offset:64 nt
	global_load_dwordx4 v[204:207], v[136:137], off offset:512 nt
	s_mov_b64 s[60:61], s[68:69]
	v_lshl_add_u64 v[138:139], s[60:61], 0, v[128:129]
	global_load_dwordx4 v[140:143], v[138:139], off
	global_load_dwordx4 v[132:135], v[138:139], off offset:64
	global_load_dwordx4 v[128:131], v[138:139], off offset:512
	global_load_dwordx4 v[222:225], v[136:137], off offset:576 nt
	v_and_b32_e32 v145, 64, v192
	global_load_dwordx4 v[136:139], v[138:139], off offset:576
	v_xor_b32_e32 v144, 1, v192
	v_add_u32_e32 v194, 64, v145
	v_add_u32_e32 v186, 16, v184
	v_cmp_lt_i32_e64 s[4:5], v144, v194
	v_ashrrev_i32_e32 v187, 31, v186
	ds_bpermute_b32 v188, v193, v124
	v_cndmask_b32_e64 v195, v192, v144, s[4:5]
	v_lshlrev_b64 v[144:145], 13, v[186:187]
	v_lshl_add_u64 v[144:145], v[182:183], 0, v[144:145]
	global_load_dwordx4 v[156:159], v[144:145], off nt
	global_load_dwordx4 v[152:155], v[144:145], off offset:64 nt
	global_load_dwordx4 v[148:151], v[144:145], off offset:512 nt
	s_nop 0
	global_load_dwordx4 v[144:147], v[144:145], off offset:576 nt
	ds_bpermute_b32 v189, v193, v125
	ds_bpermute_b32 v208, v193, v126
	ds_bpermute_b32 v209, v193, v127
	ds_bpermute_b32 v226, v193, v120
	ds_bpermute_b32 v227, v193, v121
	ds_bpermute_b32 v228, v193, v122
	ds_bpermute_b32 v229, v193, v123
	ds_bpermute_b32 v230, v193, v112
	ds_bpermute_b32 v231, v193, v113
	v_readlane_b32 s64, v254, 26
	v_readlane_b32 s65, v254, 27
	v_readlane_b32 s66, v254, 28
	v_readlane_b32 s67, v254, 29
	v_readlane_b32 s72, v254, 34
	v_readlane_b32 s73, v254, 35
	v_readlane_b32 s74, v254, 36
	v_readlane_b32 s75, v254, 37
	s_mov_b64 s[64:65], s[72:73]
	ds_bpermute_b32 v232, v193, v114
	ds_bpermute_b32 v233, v193, v115
	v_lshlrev_b64 v[234:235], 11, v[184:185]
	s_mov_b64 s[66:67], s[74:75]
	v_lshl_add_u64 v[234:235], v[234:235], 0, v[180:181]
	v_xor_b32_e32 v167, 2, v192
	v_lshl_add_u64 v[236:237], v[234:235], 2, s[66:67]
	v_readlane_b32 s2, v254, 54
	v_cmp_lt_i32_e64 s[4:5], v167, v194
	v_lshlrev_b32_e32 v194, 2, v195
	v_lshlrev_b64 v[234:235], 1, v[234:235]
	v_readlane_b32 s3, v254, 55
	v_or_b32_e32 v240, 32, v234
	v_mov_b32_e32 v241, v235
	v_lshl_add_u64 v[238:239], s[2:3], 0, v[234:235]
	v_lshl_add_u64 v[240:241], s[2:3], 0, v[240:241]
	v_cndmask_b32_e64 v167, v192, v167, s[4:5]
	v_lshlrev_b32_e32 v167, 2, v167
	v_cmp_eq_u32_e32 vcc, 0, v160
	v_readlane_b32 s62, v254, 24
	v_readlane_b32 s63, v254, 25
	v_readlane_b32 s70, v254, 32
	v_readlane_b32 s71, v254, 33
	s_waitcnt vmcnt(0) lgkmcnt(0)
	v_pk_add_f32 v[198:199], v[198:199], v[208:209]
	v_pk_add_f32 v[196:197], v[196:197], v[188:189]
	v_pk_add_f32 v[202:203], v[202:203], v[228:229]
	v_pk_add_f32 v[200:201], v[200:201], v[226:227]
	v_pk_add_f32 v[204:205], v[204:205], v[230:231]
	v_mul_f32_e32 v195, v197, v197
	v_mul_f32_e32 v221, v199, v199
	global_store_dwordx4 v[236:237], v[196:199], off
	v_pk_mul_f32 v[188:189], v[142:143], v[198:199]
	v_pk_mul_f32 v[208:209], v[140:141], v[196:197]
	v_mul_f32_e32 v199, v201, v201
	v_mul_f32_e32 v230, v203, v203
	v_pk_mul_f32 v[226:227], v[134:135], v[202:203]
	v_pk_mul_f32 v[228:229], v[132:133], v[200:201]
	v_fmac_f32_e32 v195, v196, v196
	v_fmac_f32_e32 v221, v198, v198
	v_cvt_pk_bf16_f32 v196, v208, v209
	v_cvt_pk_bf16_f32 v197, v188, v189
	v_fmac_f32_e32 v199, v200, v200
	v_fmac_f32_e32 v230, v202, v202
	v_pk_add_f32 v[206:207], v[206:207], v[232:233]
	v_cvt_pk_bf16_f32 v188, v228, v229
	v_cvt_pk_bf16_f32 v189, v226, v227
	v_add_f32_e32 v195, v195, v221
	global_store_dwordx2 v[238:239], v[196:197], off
	v_add_f32_e32 v196, v199, v230
	global_store_dwordx4 v[236:237], v[200:203], off offset:64
	global_store_dwordx2 v[240:241], v[188:189], off
	v_add_f32_e32 v188, v195, v196
	v_mul_f32_e32 v189, v205, v205
	v_mul_f32_e32 v195, v207, v207
	v_fmac_f32_e32 v189, v204, v204
	v_fmac_f32_e32 v195, v206, v206
	ds_bpermute_b32 v200, v193, v108
	ds_bpermute_b32 v198, v193, v110
	ds_bpermute_b32 v199, v193, v111
	ds_bpermute_b32 v201, v193, v109
	v_add_f32_e32 v189, v189, v195
	v_add_f32_e32 v195, v188, v189
	v_pk_mul_f32 v[188:189], v[130:131], v[206:207]
	v_pk_mul_f32 v[196:197], v[128:129], v[204:205]
	global_store_dwordx4 v[236:237], v[204:207], off offset:512
	v_cvt_pk_bf16_f32 v196, v196, v197
	v_cvt_pk_bf16_f32 v197, v188, v189
	v_or_b32_e32 v188, 0x100, v234
	v_mov_b32_e32 v189, v235
	v_lshl_add_u64 v[188:189], s[2:3], 0, v[188:189]
	global_store_dwordx2 v[188:189], v[196:197], off
	s_waitcnt lgkmcnt(1)
	v_pk_add_f32 v[198:199], v[224:225], v[198:199]
	s_waitcnt lgkmcnt(0)
	v_pk_add_f32 v[196:197], v[222:223], v[200:201]
	v_mul_f32_e32 v189, v199, v199
	v_mul_f32_e32 v188, v197, v197
	v_fmac_f32_e32 v188, v196, v196
	v_fmac_f32_e32 v189, v198, v198
	v_add_f32_e32 v188, v188, v189
	v_add_f32_e32 v195, v195, v188
	ds_bpermute_b32 v200, v194, v195
	v_pk_mul_f32 v[188:189], v[136:137], v[196:197]
	global_store_dwordx4 v[236:237], v[196:199], off offset:576
	v_or_b32_e32 v234, 0x120, v234
	s_nop 0
	v_cvt_pk_bf16_f32 v196, v188, v189
	s_waitcnt lgkmcnt(0)
	v_add_f32_e32 v188, v195, v200
	ds_bpermute_b32 v189, v167, v188
	v_pk_mul_f32 v[198:199], v[138:139], v[198:199]
	s_nop 0
	v_cvt_pk_bf16_f32 v197, v198, v199
	v_lshl_add_u64 v[198:199], s[2:3], 0, v[234:235]
	global_store_dwordx2 v[198:199], v[196:197], off
	s_and_saveexec_b64 s[4:5], vcc
	s_cbranch_execz .LBB0_1028
	s_waitcnt lgkmcnt(0)
	v_add_f32_e32 v195, v188, v189
	s_lshl_b32 s36, s30, 2
	v_lshlrev_b64 v[188:189], 7, v[184:185]
	s_ashr_i32 s37, s36, 31
	v_lshl_add_u64 v[188:189], s[10:11], 0, v[188:189]
	v_lshl_add_u64 v[188:189], s[36:37], 2, v[188:189]
	s_lshl_b32 s36, s45, 2
	s_mov_b32 s37, s13
	v_lshl_add_u64 v[188:189], v[188:189], 0, s[36:37]
	global_store_dword v[188:189], v195, off

.LBB0_1167:
	ds_read_b128 v[148:151], v143
	ds_read_b128 v[152:155], v143 offset:1024
	ds_read_b128 v[156:159], v143 offset:2048
	ds_read_b128 v[160:163], v143 offset:3072
	s_add_u32 s24, s22, 0xfff80080
	s_addc_u32 s25, s23, -1
	s_cmp_eq_u32 s53, 28
	s_cselect_b32 s27, s15, s25
	s_cselect_b32 s26, s49, s24
	s_cselect_b32 s25, s13, s52
	s_cselect_b32 s24, s50, s51
	v_lshl_add_u64 v[136:137], s[22:23], 0, v[128:129]
	s_add_i32 m0, s21, 0xc000
	ds_read_b128 v[164:167], v145
	ds_read_b128 v[176:179], v145 offset:1024
	ds_read_b128 v[180:183], v145 offset:2048
	ds_read_b128 v[184:187], v145 offset:3072
	ds_read_b128 v[188:191], v145 offset:4096
	ds_read_b128 v[192:195], v145 offset:5120
	ds_read_b128 v[196:199], v145 offset:6144
	ds_read_b128 v[200:203], v145 offset:7168
	global_load_lds_dwordx4 v[136:137], off
	v_lshl_add_u64 v[136:137], s[22:23], 0, v[130:131]
	s_add_i32 m0, s21, 0xe000
	s_nop 0
	global_load_lds_dwordx4 v[136:137], off
	s_waitcnt lgkmcnt(8)
	s_barrier
	s_waitcnt lgkmcnt(0)

	s_waitcnt lgkmcnt(0)
	v_mfma_f32_16x16x32_bf16 v[124:127], v[148:151], v[164:167], v[124:127]
	v_mfma_f32_16x16x32_bf16 v[120:123], v[156:159], v[164:167], v[120:123]
	v_mfma_f32_16x16x32_bf16 v[116:119], v[148:151], v[180:183], v[116:119]
	v_mfma_f32_16x16x32_bf16 v[104:107], v[156:159], v[180:183], v[104:107]
	v_mfma_f32_16x16x32_bf16 v[96:99], v[148:151], v[188:191], v[96:99]
	v_mfma_f32_16x16x32_bf16 v[88:91], v[156:159], v[188:191], v[88:91]
	v_mfma_f32_16x16x32_bf16 v[80:83], v[148:151], v[196:199], v[80:83]
	v_mfma_f32_16x16x32_bf16 v[72:75], v[156:159], v[196:199], v[72:75]
	v_mfma_f32_16x16x32_bf16 v[124:127], v[152:155], v[176:179], v[124:127]
	v_mfma_f32_16x16x32_bf16 v[120:123], v[160:163], v[176:179], v[120:123]
	v_mfma_f32_16x16x32_bf16 v[116:119], v[152:155], v[184:187], v[116:119]
	v_mfma_f32_16x16x32_bf16 v[104:107], v[160:163], v[184:187], v[104:107]
	v_mfma_f32_16x16x32_bf16 v[96:99], v[152:155], v[192:195], v[96:99]
	v_mfma_f32_16x16x32_bf16 v[88:91], v[160:163], v[192:195], v[88:91]
	v_mfma_f32_16x16x32_bf16 v[80:83], v[152:155], v[200:203], v[80:83]
	v_mfma_f32_16x16x32_bf16 v[72:75], v[160:163], v[200:203], v[72:75]

	s_barrier
	s_add_i32 s54, s45, s31
	v_lshl_add_u64 v[136:137], s[24:25], 0, v[172:173]
	s_mov_b32 m0, s54
	ds_read_b128 v[204:207], v147
	ds_read_b128 v[218:221], v147 offset:1024
	ds_read_b128 v[222:225], v147 offset:2048
	ds_read_b128 v[226:229], v147 offset:3072
	global_load_lds_dwordx4 v[136:137], off
	v_lshl_add_u64 v[140:141], s[24:25], 0, v[174:175]
	s_add_i32 m0, s54, 0x2000
	s_nop 0
	global_load_lds_dwordx4 v[140:141], off
	s_barrier
	s_waitcnt lgkmcnt(0)

	s_waitcnt lgkmcnt(0)
	v_mfma_f32_16x16x32_bf16 v[112:115], v[204:207], v[164:167], v[112:115]
	v_mfma_f32_16x16x32_bf16 v[108:111], v[222:225], v[164:167], v[108:111]
	v_mfma_f32_16x16x32_bf16 v[100:103], v[204:207], v[180:183], v[100:103]
	v_mfma_f32_16x16x32_bf16 v[92:95], v[222:225], v[180:183], v[92:95]
	v_mfma_f32_16x16x32_bf16 v[84:87], v[204:207], v[188:191], v[84:87]
	v_mfma_f32_16x16x32_bf16 v[76:79], v[222:225], v[188:191], v[76:79]
	v_mfma_f32_16x16x32_bf16 v[68:71], v[204:207], v[196:199], v[68:71]
	v_mfma_f32_16x16x32_bf16 v[64:67], v[222:225], v[196:199], v[64:67]
	v_mfma_f32_16x16x32_bf16 v[112:115], v[218:221], v[176:179], v[112:115]
	v_mfma_f32_16x16x32_bf16 v[108:111], v[226:229], v[176:179], v[108:111]
	v_mfma_f32_16x16x32_bf16 v[100:103], v[218:221], v[184:187], v[100:103]
	v_mfma_f32_16x16x32_bf16 v[92:95], v[226:229], v[184:187], v[92:95]
	v_mfma_f32_16x16x32_bf16 v[84:87], v[218:221], v[192:195], v[84:87]
	v_mfma_f32_16x16x32_bf16 v[76:79], v[226:229], v[192:195], v[76:79]
	v_mfma_f32_16x16x32_bf16 v[68:71], v[218:221], v[200:203], v[68:71]
	v_mfma_f32_16x16x32_bf16 v[64:67], v[226:229], v[200:203], v[64:67]

	s_mov_b32 m0, s21
	v_lshl_add_u64 v[208:209], s[26:27], 0, v[172:173]
	s_barrier
	ds_read_b128 v[164:167], v145 offset:16384
	ds_read_b128 v[176:179], v145 offset:17408
	ds_read_b128 v[180:183], v145 offset:18432
	ds_read_b128 v[184:187], v145 offset:19456
	ds_read_b128 v[188:191], v145 offset:20480
	ds_read_b128 v[192:195], v145 offset:21504
	ds_read_b128 v[196:199], v145 offset:22528
	ds_read_b128 v[200:203], v145 offset:23552
	global_load_lds_dwordx4 v[208:209], off
	v_lshl_add_u64 v[230:231], s[26:27], 0, v[174:175]
	s_mov_b32 m0, s35
	s_nop 0
	global_load_lds_dwordx4 v[230:231], off
	s_barrier
	s_waitcnt lgkmcnt(0)

	s_waitcnt lgkmcnt(0)
	v_mfma_f32_16x16x32_bf16 v[60:63], v[148:151], v[164:167], v[60:63]
	v_mfma_f32_16x16x32_bf16 v[56:59], v[156:159], v[164:167], v[56:59]
	v_mfma_f32_16x16x32_bf16 v[48:51], v[148:151], v[180:183], v[48:51]
	v_mfma_f32_16x16x32_bf16 v[40:43], v[156:159], v[180:183], v[40:43]
	v_mfma_f32_16x16x32_bf16 v[32:35], v[148:151], v[188:191], v[32:35]
	v_mfma_f32_16x16x32_bf16 v[24:27], v[156:159], v[188:191], v[24:27]
	v_mfma_f32_16x16x32_bf16 v[16:19], v[148:151], v[196:199], v[16:19]
	v_mfma_f32_16x16x32_bf16 v[8:11], v[156:159], v[196:199], v[8:11]
	v_mfma_f32_16x16x32_bf16 v[60:63], v[152:155], v[176:179], v[60:63]
	v_mfma_f32_16x16x32_bf16 v[56:59], v[160:163], v[176:179], v[56:59]
	v_mfma_f32_16x16x32_bf16 v[48:51], v[152:155], v[184:187], v[48:51]
	v_mfma_f32_16x16x32_bf16 v[40:43], v[160:163], v[184:187], v[40:43]
	v_mfma_f32_16x16x32_bf16 v[32:35], v[152:155], v[192:195], v[32:35]
	v_mfma_f32_16x16x32_bf16 v[24:27], v[160:163], v[192:195], v[24:27]
	v_mfma_f32_16x16x32_bf16 v[16:19], v[152:155], v[200:203], v[16:19]
	v_mfma_f32_16x16x32_bf16 v[8:11], v[160:163], v[200:203], v[8:11]

	s_barrier
	s_add_u32 s54, s24, 0x80000
	s_addc_u32 s55, s25, 0
	s_add_i32 s56, s46, s31
	v_lshl_add_u64 v[148:149], s[54:55], 0, v[172:173]
	s_mov_b32 m0, s56
	s_nop 0
	global_load_lds_dwordx4 v[148:149], off
	v_lshl_add_u64 v[148:149], s[54:55], 0, v[174:175]
	s_add_i32 m0, s56, 0x2000
	s_nop 0
	global_load_lds_dwordx4 v[148:149], off
	s_waitcnt vmcnt(6)
	s_barrier

	v_mfma_f32_16x16x32_bf16 v[52:55], v[204:207], v[164:167], v[52:55]
	v_mfma_f32_16x16x32_bf16 v[44:47], v[222:225], v[164:167], v[44:47]
	v_mfma_f32_16x16x32_bf16 v[36:39], v[204:207], v[180:183], v[36:39]
	v_mfma_f32_16x16x32_bf16 v[28:31], v[222:225], v[180:183], v[28:31]
	v_mfma_f32_16x16x32_bf16 v[20:23], v[204:207], v[188:191], v[20:23]
	v_mfma_f32_16x16x32_bf16 v[12:15], v[222:225], v[188:191], v[12:15]
	v_mfma_f32_16x16x32_bf16 v[4:7], v[204:207], v[196:199], v[4:7]
	v_mfma_f32_16x16x32_bf16 v[0:3], v[222:225], v[196:199], v[0:3]
	v_mfma_f32_16x16x32_bf16 v[52:55], v[218:221], v[176:179], v[52:55]
	v_mfma_f32_16x16x32_bf16 v[44:47], v[226:229], v[176:179], v[44:47]
	v_mfma_f32_16x16x32_bf16 v[36:39], v[218:221], v[184:187], v[36:39]
	v_mfma_f32_16x16x32_bf16 v[28:31], v[226:229], v[184:187], v[28:31]
	v_mfma_f32_16x16x32_bf16 v[20:23], v[218:221], v[192:195], v[20:23]
	v_mfma_f32_16x16x32_bf16 v[12:15], v[226:229], v[192:195], v[12:15]
	v_mfma_f32_16x16x32_bf16 v[4:7], v[218:221], v[200:203], v[4:7]
	v_mfma_f32_16x16x32_bf16 v[0:3], v[226:229], v[200:203], v[0:3]

	s_add_i32 s54, 0, 0x18000
	v_add_u32_e32 v138, s54, v139
	s_barrier
	ds_read_b128 v[148:151], v138
	ds_read_b128 v[152:155], v138 offset:1024
	ds_read_b128 v[156:159], v138 offset:2048
	ds_read_b128 v[160:163], v138 offset:3072
	s_add_u32 s26, s26, 0x80000
	s_addc_u32 s27, s27, 0
	s_mov_b32 m0, s36
	v_lshl_add_u64 v[204:205], s[26:27], 0, v[172:173]
	ds_read_b128 v[164:167], v145 offset:32768
	ds_read_b128 v[176:179], v145 offset:33792
	ds_read_b128 v[180:183], v145 offset:34816
	ds_read_b128 v[184:187], v145 offset:35840
	ds_read_b128 v[188:191], v145 offset:36864
	ds_read_b128 v[192:195], v145 offset:37888
	ds_read_b128 v[196:199], v145 offset:38912
	ds_read_b128 v[200:203], v145 offset:39936
	global_load_lds_dwordx4 v[204:205], off
	v_lshl_add_u64 v[204:205], s[26:27], 0, v[174:175]
	s_mov_b32 m0, s37
	s_nop 0
	global_load_lds_dwordx4 v[204:205], off
	s_waitcnt lgkmcnt(8)
	s_barrier
	s_waitcnt lgkmcnt(0)

	s_waitcnt lgkmcnt(0)
	v_mfma_f32_16x16x32_bf16 v[124:127], v[148:151], v[164:167], v[124:127]
	v_mfma_f32_16x16x32_bf16 v[120:123], v[156:159], v[164:167], v[120:123]
	v_mfma_f32_16x16x32_bf16 v[116:119], v[148:151], v[180:183], v[116:119]
	v_mfma_f32_16x16x32_bf16 v[104:107], v[156:159], v[180:183], v[104:107]
	v_mfma_f32_16x16x32_bf16 v[96:99], v[148:151], v[188:191], v[96:99]
	v_mfma_f32_16x16x32_bf16 v[88:91], v[156:159], v[188:191], v[88:91]
	v_mfma_f32_16x16x32_bf16 v[80:83], v[148:151], v[196:199], v[80:83]
	v_mfma_f32_16x16x32_bf16 v[72:75], v[156:159], v[196:199], v[72:75]
	v_mfma_f32_16x16x32_bf16 v[124:127], v[152:155], v[176:179], v[124:127]
	v_mfma_f32_16x16x32_bf16 v[120:123], v[160:163], v[176:179], v[120:123]
	v_mfma_f32_16x16x32_bf16 v[116:119], v[152:155], v[184:187], v[116:119]
	v_mfma_f32_16x16x32_bf16 v[104:107], v[160:163], v[184:187], v[104:107]
	v_mfma_f32_16x16x32_bf16 v[96:99], v[152:155], v[192:195], v[96:99]
	v_mfma_f32_16x16x32_bf16 v[88:91], v[160:163], v[192:195], v[88:91]
	v_mfma_f32_16x16x32_bf16 v[80:83], v[152:155], v[200:203], v[80:83]
	v_mfma_f32_16x16x32_bf16 v[72:75], v[160:163], v[200:203], v[72:75]

	s_barrier
	s_add_i32 s26, 0, 0x1c000
	s_add_i32 s27, s54, s31
	v_add_u32_e32 v138, s26, v139
	v_lshl_add_u64 v[136:137], v[136:137], 0, s[10:11]
	s_mov_b32 m0, s27
	ds_read_b128 v[204:207], v138
	ds_read_b128 v[218:221], v138 offset:1024
	ds_read_b128 v[222:225], v138 offset:2048
	ds_read_b128 v[226:229], v138 offset:3072
	global_load_lds_dwordx4 v[136:137], off
	v_lshl_add_u64 v[136:137], v[140:141], 0, s[10:11]
	s_add_i32 m0, s27, 0x2000
	s_nop 0
	global_load_lds_dwordx4 v[136:137], off
	s_barrier
	s_waitcnt lgkmcnt(0)

	s_waitcnt lgkmcnt(0)
	v_mfma_f32_16x16x32_bf16 v[112:115], v[204:207], v[164:167], v[112:115]
	v_mfma_f32_16x16x32_bf16 v[108:111], v[222:225], v[164:167], v[108:111]
	v_mfma_f32_16x16x32_bf16 v[100:103], v[204:207], v[180:183], v[100:103]
	v_mfma_f32_16x16x32_bf16 v[92:95], v[222:225], v[180:183], v[92:95]
	v_mfma_f32_16x16x32_bf16 v[84:87], v[204:207], v[188:191], v[84:87]
	v_mfma_f32_16x16x32_bf16 v[76:79], v[222:225], v[188:191], v[76:79]
	v_mfma_f32_16x16x32_bf16 v[68:71], v[204:207], v[196:199], v[68:71]
	v_mfma_f32_16x16x32_bf16 v[64:67], v[222:225], v[196:199], v[64:67]
	v_mfma_f32_16x16x32_bf16 v[112:115], v[218:221], v[176:179], v[112:115]
	v_mfma_f32_16x16x32_bf16 v[108:111], v[226:229], v[176:179], v[108:111]
	v_mfma_f32_16x16x32_bf16 v[100:103], v[218:221], v[184:187], v[100:103]
	v_mfma_f32_16x16x32_bf16 v[92:95], v[226:229], v[184:187], v[92:95]
	v_mfma_f32_16x16x32_bf16 v[84:87], v[218:221], v[192:195], v[84:87]
	v_mfma_f32_16x16x32_bf16 v[76:79], v[226:229], v[192:195], v[76:79]
	v_mfma_f32_16x16x32_bf16 v[68:71], v[218:221], v[200:203], v[68:71]
	v_mfma_f32_16x16x32_bf16 v[64:67], v[226:229], v[200:203], v[64:67]

	s_mov_b32 m0, s41
	v_lshl_add_u64 v[136:137], v[208:209], 0, s[10:11]
	s_barrier
	ds_read_b128 v[164:167], v145 offset:49152
	ds_read_b128 v[176:179], v145 offset:50176
	ds_read_b128 v[180:183], v145 offset:51200
	ds_read_b128 v[184:187], v145 offset:52224
	ds_read_b128 v[188:191], v145 offset:53248
	ds_read_b128 v[192:195], v145 offset:54272
	ds_read_b128 v[196:199], v145 offset:55296
	ds_read_b128 v[200:203], v145 offset:56320
	global_load_lds_dwordx4 v[136:137], off
	v_lshl_add_u64 v[136:137], v[230:231], 0, s[10:11]
	s_mov_b32 m0, s42
	s_nop 0
	global_load_lds_dwordx4 v[136:137], off
	s_barrier
	s_waitcnt lgkmcnt(0)

	s_waitcnt lgkmcnt(0)
	v_mfma_f32_16x16x32_bf16 v[60:63], v[148:151], v[164:167], v[60:63]
	v_mfma_f32_16x16x32_bf16 v[56:59], v[156:159], v[164:167], v[56:59]
	v_mfma_f32_16x16x32_bf16 v[48:51], v[148:151], v[180:183], v[48:51]
	v_mfma_f32_16x16x32_bf16 v[40:43], v[156:159], v[180:183], v[40:43]
	v_mfma_f32_16x16x32_bf16 v[32:35], v[148:151], v[188:191], v[32:35]
	v_mfma_f32_16x16x32_bf16 v[24:27], v[156:159], v[188:191], v[24:27]
	v_mfma_f32_16x16x32_bf16 v[16:19], v[148:151], v[196:199], v[16:19]
	v_mfma_f32_16x16x32_bf16 v[8:11], v[156:159], v[196:199], v[8:11]
	v_mfma_f32_16x16x32_bf16 v[60:63], v[152:155], v[176:179], v[60:63]
	v_mfma_f32_16x16x32_bf16 v[56:59], v[160:163], v[176:179], v[56:59]
	v_mfma_f32_16x16x32_bf16 v[48:51], v[152:155], v[184:187], v[48:51]
	v_mfma_f32_16x16x32_bf16 v[40:43], v[160:163], v[184:187], v[40:43]
	v_mfma_f32_16x16x32_bf16 v[32:35], v[152:155], v[192:195], v[32:35]
	v_mfma_f32_16x16x32_bf16 v[24:27], v[160:163], v[192:195], v[24:27]
	v_mfma_f32_16x16x32_bf16 v[16:19], v[152:155], v[200:203], v[16:19]
	v_mfma_f32_16x16x32_bf16 v[8:11], v[160:163], v[200:203], v[8:11]

	s_barrier
	s_add_u32 s24, s24, 0x80080
	s_addc_u32 s25, s25, 0
	s_add_i32 s26, s26, s31
	v_lshl_add_u64 v[136:137], s[24:25], 0, v[172:173]
	s_mov_b32 m0, s26
	s_nop 0
	global_load_lds_dwordx4 v[136:137], off
	v_lshl_add_u64 v[136:137], s[24:25], 0, v[174:175]
	s_add_i32 m0, s26, 0x2000
	s_nop 0
	global_load_lds_dwordx4 v[136:137], off
	s_waitcnt vmcnt(6)
	s_barrier

	v_mfma_f32_16x16x32_bf16 v[52:55], v[204:207], v[164:167], v[52:55]
	v_mfma_f32_16x16x32_bf16 v[44:47], v[222:225], v[164:167], v[44:47]
	v_mfma_f32_16x16x32_bf16 v[36:39], v[204:207], v[180:183], v[36:39]
	v_mfma_f32_16x16x32_bf16 v[28:31], v[222:225], v[180:183], v[28:31]
	v_mfma_f32_16x16x32_bf16 v[20:23], v[204:207], v[188:191], v[20:23]
	v_mfma_f32_16x16x32_bf16 v[12:15], v[222:225], v[188:191], v[12:15]
	v_mfma_f32_16x16x32_bf16 v[4:7], v[204:207], v[196:199], v[4:7]
	v_mfma_f32_16x16x32_bf16 v[0:3], v[222:225], v[196:199], v[0:3]
	v_mfma_f32_16x16x32_bf16 v[52:55], v[218:221], v[176:179], v[52:55]
	v_mfma_f32_16x16x32_bf16 v[44:47], v[226:229], v[176:179], v[44:47]
	v_mfma_f32_16x16x32_bf16 v[36:39], v[218:221], v[184:187], v[36:39]
	v_mfma_f32_16x16x32_bf16 v[28:31], v[226:229], v[184:187], v[28:31]
	v_mfma_f32_16x16x32_bf16 v[20:23], v[218:221], v[192:195], v[20:23]
	v_mfma_f32_16x16x32_bf16 v[12:15], v[226:229], v[192:195], v[12:15]
	v_mfma_f32_16x16x32_bf16 v[4:7], v[218:221], v[200:203], v[4:7]
	v_mfma_f32_16x16x32_bf16 v[0:3], v[226:229], v[200:203], v[0:3]

	s_add_i32 s53, s53, 2
	s_add_u32 s22, s22, 0x100
	s_addc_u32 s23, s23, 0
	s_add_u32 s51, s51, 0x100
	s_addc_u32 s52, s52, 0
	s_cmp_gt_u32 s53, 29
	s_barrier
	s_cbranch_scc0 .LBB0_1167
	s_lshl_b32 s13, s20, 8
	v_mov_b32_e32 v138, v210
	v_mov_b32_e32 v142, v169
	s_add_i32 s13, s13, s39
	s_lshl_b32 s15, s48, 7
	v_add_u32_e32 v136, s13, v142
	v_ashrrev_i32_e32 v137, 31, v136
	v_lshl_add_u64 v[140:141], v[136:137], 2, s[2:3]
	global_load_dword v154, v[140:141], off
	global_load_dword v152, v[140:141], off offset:64
	v_lshl_add_u32 v138, v138, 4, v142
	v_and_b32_e32 v142, 3, v142
	v_ashrrev_i32_e32 v144, 2, v138
	v_and_b32_e32 v138, -4, v138
	v_lshl_or_b32 v146, v142, 2, s15
	v_add_u32_e32 v151, s13, v144
	v_lshl_add_u32 v149, v142, 6, v138
	v_or_b32_e32 v156, s40, v146
	global_load_dword v150, v[140:141], off offset:128
	global_load_dword v148, v[140:141], off offset:192
	global_load_dword v146, v[140:141], off offset:512
	global_load_dword v144, v[140:141], off offset:576
	global_load_dword v142, v[140:141], off offset:640
	global_load_dword v138, v[140:141], off offset:704
	v_mov_b64_e32 v[136:137], s[0:1]
	v_ashrrev_i32_e32 v157, 31, v156
	v_mad_i64_i32 v[158:159], s[22:23], v151, s47, v[136:137]
	v_lshlrev_b64 v[140:141], 1, v[156:157]
	v_lshl_add_u64 v[156:157], v[158:159], 0, v[140:141]
	v_add_u32_e32 v153, 16, v151
	s_and_b64 vcc, exec, s[4:5]
	s_mov_b32 s48, s12
	s_mov_b32 s20, s14
	s_mov_b64 s[24:25], s[18:19]
	s_waitcnt vmcnt(0)
	v_pk_mul_f32 v[126:127], v[126:127], v[154:155] op_sel_hi:[1,0]
	v_pk_mul_f32 v[124:125], v[124:125], v[154:155] op_sel_hi:[1,0]
	v_pk_mul_f32 v[114:115], v[114:115], v[154:155] op_sel_hi:[1,0]
	v_pk_mul_f32 v[112:113], v[112:113], v[154:155] op_sel_hi:[1,0]
	v_pk_mul_f32 v[122:123], v[122:123], v[154:155] op_sel_hi:[1,0]
	v_pk_mul_f32 v[120:121], v[120:121], v[154:155] op_sel_hi:[1,0]
	v_pk_mul_f32 v[110:111], v[110:111], v[154:155] op_sel_hi:[1,0]
	v_pk_mul_f32 v[108:109], v[108:109], v[154:155] op_sel_hi:[1,0]
	v_mul_f32_e32 v154, 0xbfb8aa3b, v124
	v_mul_f32_e32 v155, 0xbfb8aa3b, v125
	v_mul_f32_e32 v158, 0xbfb8aa3b, v126
	v_mul_f32_e32 v159, 0xbfb8aa3b, v127
	v_mul_f32_e32 v160, 0xbfb8aa3b, v120
	v_mul_f32_e32 v161, 0xbfb8aa3b, v121
	v_mul_f32_e32 v162, 0xbfb8aa3b, v122
	v_mul_f32_e32 v163, 0xbfb8aa3b, v123
	v_exp_f32_e32 v154, v154
	v_exp_f32_e32 v155, v155
	v_exp_f32_e32 v158, v158
	v_exp_f32_e32 v159, v159
	v_exp_f32_e32 v160, v160
	v_exp_f32_e32 v161, v161
	v_exp_f32_e32 v162, v162
	v_exp_f32_e32 v163, v163
	v_add_f32_e32 v154, 1.0, v154
	v_add_f32_e32 v155, 1.0, v155
	v_add_f32_e32 v158, 1.0, v158
	v_add_f32_e32 v159, 1.0, v159
	v_add_f32_e32 v160, 1.0, v160
	v_add_f32_e32 v161, 1.0, v161
	v_add_f32_e32 v162, 1.0, v162
	v_add_f32_e32 v163, 1.0, v163
	v_rcp_f32_e32 v154, v154
	v_rcp_f32_e32 v155, v155
	v_rcp_f32_e32 v158, v158
	v_rcp_f32_e32 v159, v159
	v_rcp_f32_e32 v160, v160
	v_rcp_f32_e32 v161, v161
	v_rcp_f32_e32 v162, v162
	v_rcp_f32_e32 v163, v163
	v_pk_mul_f32 v[124:125], v[124:125], v[154:155]
	v_pk_mul_f32 v[126:127], v[126:127], v[158:159]
	v_pk_mul_f32 v[120:121], v[120:121], v[160:161]
	v_pk_mul_f32 v[122:123], v[122:123], v[162:163]
	v_pk_mul_f32 v[112:113], v[112:113], v[124:125]
	v_pk_mul_f32 v[114:115], v[114:115], v[126:127]
	v_pk_mul_f32 v[118:119], v[118:119], v[152:153] op_sel_hi:[1,0]
	v_pk_mul_f32 v[116:117], v[116:117], v[152:153] op_sel_hi:[1,0]
	v_pk_mul_f32 v[108:109], v[108:109], v[120:121]
	v_pk_mul_f32 v[110:111], v[110:111], v[122:123]
	v_cvt_pk_bf16_f32 v112, v112, v113
	v_cvt_pk_bf16_f32 v113, v114, v115
	v_mul_f32_e32 v164, 0xbfb8aa3b, v116
	v_mul_f32_e32 v165, 0xbfb8aa3b, v117
	v_mul_f32_e32 v166, 0xbfb8aa3b, v118
	v_mul_f32_e32 v167, 0xbfb8aa3b, v119
	v_cvt_pk_bf16_f32 v114, v108, v109
	v_cvt_pk_bf16_f32 v111, v110, v111
	ds_bpermute_b32 v108, v149, v112
	ds_bpermute_b32 v109, v149, v113
	v_exp_f32_e32 v164, v164
	v_exp_f32_e32 v165, v165
	v_exp_f32_e32 v166, v166
	v_exp_f32_e32 v167, v167
	ds_bpermute_b32 v110, v149, v114
	ds_bpermute_b32 v111, v149, v111
	v_add_f32_e32 v164, 1.0, v164
	v_add_f32_e32 v113, 1.0, v165
	s_waitcnt lgkmcnt(0)
	global_store_dwordx2 v[156:157], v[108:109], off
	global_store_dwordx2 v[156:157], v[110:111], off offset:32
	v_add_f32_e32 v108, 1.0, v166
	v_add_f32_e32 v109, 1.0, v167
	v_rcp_f32_e32 v112, v164
	v_rcp_f32_e32 v113, v113
	v_rcp_f32_e32 v108, v108
	v_rcp_f32_e32 v109, v109
	v_pk_mul_f32 v[102:103], v[102:103], v[152:153] op_sel_hi:[1,0]
	v_pk_mul_f32 v[100:101], v[100:101], v[152:153] op_sel_hi:[1,0]
	v_pk_mul_f32 v[110:111], v[116:117], v[112:113]
	v_pk_mul_f32 v[108:109], v[118:119], v[108:109]
	v_pk_mul_f32 v[100:101], v[100:101], v[110:111]
	v_pk_mul_f32 v[102:103], v[102:103], v[108:109]
	v_cvt_pk_bf16_f32 v100, v100, v101
	v_cvt_pk_bf16_f32 v101, v102, v103
	v_pk_mul_f32 v[102:103], v[106:107], v[152:153] op_sel_hi:[1,0]
	v_pk_mul_f32 v[104:105], v[104:105], v[152:153] op_sel_hi:[1,0]
	v_mul_f32_e32 v108, 0xbfb8aa3b, v102
	v_mul_f32_e32 v106, 0xbfb8aa3b, v104
	v_mul_f32_e32 v107, 0xbfb8aa3b, v105
	v_mul_f32_e32 v109, 0xbfb8aa3b, v103
	v_exp_f32_e32 v106, v106
	v_exp_f32_e32 v107, v107
	v_exp_f32_e32 v108, v108
	v_exp_f32_e32 v109, v109
	v_add_f32_e32 v106, 1.0, v106
	v_add_f32_e32 v107, 1.0, v107
	v_add_f32_e32 v108, 1.0, v108
	v_add_f32_e32 v109, 1.0, v109
	v_rcp_f32_e32 v106, v106
	v_rcp_f32_e32 v107, v107
	v_rcp_f32_e32 v108, v108
	v_rcp_f32_e32 v109, v109
	v_pk_mul_f32 v[94:95], v[94:95], v[152:153] op_sel_hi:[1,0]
	v_pk_mul_f32 v[92:93], v[92:93], v[152:153] op_sel_hi:[1,0]
	v_pk_mul_f32 v[104:105], v[104:105], v[106:107]
	v_pk_mul_f32 v[102:103], v[102:103], v[108:109]
	v_pk_mul_f32 v[92:93], v[92:93], v[104:105]
	v_pk_mul_f32 v[94:95], v[94:95], v[102:103]
	ds_bpermute_b32 v100, v149, v100
	ds_bpermute_b32 v101, v149, v101
	v_cvt_pk_bf16_f32 v92, v92, v93
	v_cvt_pk_bf16_f32 v93, v94, v95
	ds_bpermute_b32 v92, v149, v92
	ds_bpermute_b32 v93, v149, v93
	v_mad_i64_i32 v[94:95], s[22:23], v153, s47, v[136:137]
	v_lshl_add_u64 v[94:95], v[94:95], 0, v[140:141]
	s_waitcnt lgkmcnt(2)
	global_store_dwordx2 v[94:95], v[100:101], off
	s_waitcnt lgkmcnt(0)
	global_store_dwordx2 v[94:95], v[92:93], off offset:32
	v_pk_mul_f32 v[92:93], v[98:99], v[150:151] op_sel_hi:[1,0]
	v_pk_mul_f32 v[94:95], v[96:97], v[150:151] op_sel_hi:[1,0]
	v_mul_f32_e32 v98, 0xbfb8aa3b, v92
	v_mul_f32_e32 v96, 0xbfb8aa3b, v94
	v_mul_f32_e32 v97, 0xbfb8aa3b, v95
	v_mul_f32_e32 v99, 0xbfb8aa3b, v93
	v_exp_f32_e32 v96, v96
	v_exp_f32_e32 v97, v97
	v_exp_f32_e32 v98, v98
	v_exp_f32_e32 v99, v99
	v_add_f32_e32 v96, 1.0, v96
	v_add_f32_e32 v97, 1.0, v97
	v_add_f32_e32 v98, 1.0, v98
	v_add_f32_e32 v99, 1.0, v99
	v_rcp_f32_e32 v96, v96
	v_rcp_f32_e32 v97, v97
	v_rcp_f32_e32 v98, v98
	v_rcp_f32_e32 v99, v99
	v_pk_mul_f32 v[86:87], v[86:87], v[150:151] op_sel_hi:[1,0]
	v_pk_mul_f32 v[84:85], v[84:85], v[150:151] op_sel_hi:[1,0]
	v_pk_mul_f32 v[94:95], v[94:95], v[96:97]
	v_pk_mul_f32 v[92:93], v[92:93], v[98:99]
	v_pk_mul_f32 v[84:85], v[84:85], v[94:95]
	v_pk_mul_f32 v[86:87], v[86:87], v[92:93]
	v_cvt_pk_bf16_f32 v84, v84, v85
	v_cvt_pk_bf16_f32 v85, v86, v87
	v_pk_mul_f32 v[86:87], v[90:91], v[150:151] op_sel_hi:[1,0]
	v_pk_mul_f32 v[88:89], v[88:89], v[150:151] op_sel_hi:[1,0]
	v_mul_f32_e32 v92, 0xbfb8aa3b, v86
	v_mul_f32_e32 v90, 0xbfb8aa3b, v88
	v_mul_f32_e32 v91, 0xbfb8aa3b, v89
	v_mul_f32_e32 v93, 0xbfb8aa3b, v87
	v_exp_f32_e32 v90, v90
	v_exp_f32_e32 v91, v91
	v_exp_f32_e32 v92, v92
	v_exp_f32_e32 v93, v93
	v_add_f32_e32 v90, 1.0, v90
	v_add_f32_e32 v91, 1.0, v91
	v_add_f32_e32 v92, 1.0, v92
	v_add_f32_e32 v93, 1.0, v93
	v_rcp_f32_e32 v90, v90
	v_rcp_f32_e32 v91, v91
	v_rcp_f32_e32 v92, v92
	v_rcp_f32_e32 v93, v93
	v_pk_mul_f32 v[78:79], v[78:79], v[150:151] op_sel_hi:[1,0]
	v_pk_mul_f32 v[76:77], v[76:77], v[150:151] op_sel_hi:[1,0]
	v_pk_mul_f32 v[88:89], v[88:89], v[90:91]
	v_pk_mul_f32 v[86:87], v[86:87], v[92:93]
	v_pk_mul_f32 v[76:77], v[76:77], v[88:89]
	v_pk_mul_f32 v[78:79], v[78:79], v[86:87]
	ds_bpermute_b32 v84, v149, v84
	ds_bpermute_b32 v85, v149, v85
	v_cvt_pk_bf16_f32 v76, v76, v77
	v_cvt_pk_bf16_f32 v77, v78, v79
	ds_bpermute_b32 v76, v149, v76
	ds_bpermute_b32 v77, v149, v77
	v_add_u32_e32 v100, 32, v151
	v_mad_i64_i32 v[78:79], s[22:23], v100, s47, v[136:137]
	v_lshl_add_u64 v[78:79], v[78:79], 0, v[140:141]
	s_waitcnt lgkmcnt(2)
	global_store_dwordx2 v[78:79], v[84:85], off
	s_waitcnt lgkmcnt(0)
	global_store_dwordx2 v[78:79], v[76:77], off offset:32
	v_pk_mul_f32 v[76:77], v[82:83], v[148:149] op_sel_hi:[1,0]
	v_pk_mul_f32 v[78:79], v[80:81], v[148:149] op_sel_hi:[1,0]
	v_mul_f32_e32 v82, 0xbfb8aa3b, v76
	v_mul_f32_e32 v80, 0xbfb8aa3b, v78
	v_mul_f32_e32 v81, 0xbfb8aa3b, v79
	v_mul_f32_e32 v83, 0xbfb8aa3b, v77
	v_exp_f32_e32 v80, v80
	v_exp_f32_e32 v81, v81
	v_exp_f32_e32 v82, v82
	v_exp_f32_e32 v83, v83
	v_add_f32_e32 v80, 1.0, v80
	v_add_f32_e32 v81, 1.0, v81
	v_add_f32_e32 v82, 1.0, v82
	v_add_f32_e32 v83, 1.0, v83
	v_rcp_f32_e32 v80, v80
	v_rcp_f32_e32 v81, v81
	v_rcp_f32_e32 v82, v82
	v_rcp_f32_e32 v83, v83
	v_pk_mul_f32 v[70:71], v[70:71], v[148:149] op_sel_hi:[1,0]
	v_pk_mul_f32 v[68:69], v[68:69], v[148:149] op_sel_hi:[1,0]
	v_pk_mul_f32 v[78:79], v[78:79], v[80:81]
	v_pk_mul_f32 v[76:77], v[76:77], v[82:83]
	v_pk_mul_f32 v[68:69], v[68:69], v[78:79]
	v_pk_mul_f32 v[70:71], v[70:71], v[76:77]
	v_cvt_pk_bf16_f32 v68, v68, v69
	v_cvt_pk_bf16_f32 v69, v70, v71
	v_pk_mul_f32 v[70:71], v[74:75], v[148:149] op_sel_hi:[1,0]
	v_pk_mul_f32 v[72:73], v[72:73], v[148:149] op_sel_hi:[1,0]
	v_mul_f32_e32 v76, 0xbfb8aa3b, v70
	v_mul_f32_e32 v74, 0xbfb8aa3b, v72
	v_mul_f32_e32 v75, 0xbfb8aa3b, v73
	v_mul_f32_e32 v77, 0xbfb8aa3b, v71
	v_exp_f32_e32 v74, v74
	v_exp_f32_e32 v75, v75
	v_exp_f32_e32 v76, v76
	v_exp_f32_e32 v77, v77
	v_add_f32_e32 v74, 1.0, v74
	v_add_f32_e32 v75, 1.0, v75
	v_add_f32_e32 v76, 1.0, v76
	v_add_f32_e32 v77, 1.0, v77
	v_rcp_f32_e32 v74, v74
	v_rcp_f32_e32 v75, v75
	v_rcp_f32_e32 v76, v76
	v_rcp_f32_e32 v77, v77
	v_pk_mul_f32 v[66:67], v[66:67], v[148:149] op_sel_hi:[1,0]
	v_pk_mul_f32 v[64:65], v[64:65], v[148:149] op_sel_hi:[1,0]
	v_pk_mul_f32 v[72:73], v[72:73], v[74:75]
	v_pk_mul_f32 v[70:71], v[70:71], v[76:77]
	v_pk_mul_f32 v[64:65], v[64:65], v[72:73]
	v_pk_mul_f32 v[66:67], v[66:67], v[70:71]
	ds_bpermute_b32 v68, v149, v68
	ds_bpermute_b32 v69, v149, v69
	v_cvt_pk_bf16_f32 v64, v64, v65
	v_cvt_pk_bf16_f32 v65, v66, v67
	ds_bpermute_b32 v64, v149, v64
	ds_bpermute_b32 v65, v149, v65
	v_add_u32_e32 v84, 48, v151
	v_mad_i64_i32 v[66:67], s[22:23], v84, s47, v[136:137]
	v_lshl_add_u64 v[66:67], v[66:67], 0, v[140:141]
	v_pk_mul_f32 v[60:61], v[60:61], v[146:147] op_sel_hi:[1,0]
	s_waitcnt lgkmcnt(2)
	global_store_dwordx2 v[66:67], v[68:69], off
	s_waitcnt lgkmcnt(0)
	global_store_dwordx2 v[66:67], v[64:65], off offset:32
	v_pk_mul_f32 v[62:63], v[62:63], v[146:147] op_sel_hi:[1,0]
	v_mul_f32_e32 v64, 0xbfb8aa3b, v60
	v_mul_f32_e32 v65, 0xbfb8aa3b, v61
	v_exp_f32_e32 v64, v64
	v_exp_f32_e32 v65, v65
	v_mul_f32_e32 v66, 0xbfb8aa3b, v62
	v_mul_f32_e32 v67, 0xbfb8aa3b, v63
	v_exp_f32_e32 v66, v66
	v_exp_f32_e32 v67, v67
	v_add_f32_e32 v64, 1.0, v64
	v_add_f32_e32 v65, 1.0, v65
	v_rcp_f32_e32 v64, v64
	v_rcp_f32_e32 v65, v65
	v_add_f32_e32 v66, 1.0, v66
	v_add_f32_e32 v67, 1.0, v67
	v_rcp_f32_e32 v66, v66
	v_rcp_f32_e32 v67, v67
	v_pk_mul_f32 v[52:53], v[52:53], v[146:147] op_sel_hi:[1,0]
	v_pk_mul_f32 v[60:61], v[60:61], v[64:65]
	v_pk_mul_f32 v[54:55], v[54:55], v[146:147] op_sel_hi:[1,0]
	v_pk_mul_f32 v[52:53], v[52:53], v[60:61]
	v_pk_mul_f32 v[60:61], v[62:63], v[66:67]
	v_cvt_pk_bf16_f32 v52, v52, v53
	v_pk_mul_f32 v[54:55], v[54:55], v[60:61]
	v_pk_mul_f32 v[56:57], v[56:57], v[146:147] op_sel_hi:[1,0]
	v_cvt_pk_bf16_f32 v53, v54, v55
	v_pk_mul_f32 v[54:55], v[58:59], v[146:147] op_sel_hi:[1,0]
	v_mul_f32_e32 v58, 0xbfb8aa3b, v56
	v_mul_f32_e32 v59, 0xbfb8aa3b, v57
	v_mul_f32_e32 v60, 0xbfb8aa3b, v54
	v_mul_f32_e32 v61, 0xbfb8aa3b, v55
	v_exp_f32_e32 v58, v58
	v_exp_f32_e32 v59, v59
	v_exp_f32_e32 v60, v60
	v_exp_f32_e32 v61, v61
	v_add_f32_e32 v58, 1.0, v58
	v_add_f32_e32 v59, 1.0, v59
	v_add_f32_e32 v60, 1.0, v60
	v_add_f32_e32 v61, 1.0, v61
	v_rcp_f32_e32 v58, v58
	v_rcp_f32_e32 v59, v59
	v_rcp_f32_e32 v60, v60
	v_rcp_f32_e32 v61, v61
	v_pk_mul_f32 v[46:47], v[46:47], v[146:147] op_sel_hi:[1,0]
	v_pk_mul_f32 v[44:45], v[44:45], v[146:147] op_sel_hi:[1,0]
	v_pk_mul_f32 v[56:57], v[56:57], v[58:59]
	v_pk_mul_f32 v[54:55], v[54:55], v[60:61]
	v_pk_mul_f32 v[44:45], v[44:45], v[56:57]
	v_pk_mul_f32 v[46:47], v[46:47], v[54:55]
	ds_bpermute_b32 v52, v149, v52
	ds_bpermute_b32 v53, v149, v53
	v_cvt_pk_bf16_f32 v44, v44, v45
	v_cvt_pk_bf16_f32 v45, v46, v47
	ds_bpermute_b32 v44, v149, v44
	ds_bpermute_b32 v45, v149, v45
	v_add_u32_e32 v68, 0x80, v151
	v_mad_i64_i32 v[46:47], s[22:23], v68, s47, v[136:137]
	v_lshl_add_u64 v[46:47], v[46:47], 0, v[140:141]
	s_waitcnt lgkmcnt(2)
	global_store_dwordx2 v[46:47], v[52:53], off
	s_waitcnt lgkmcnt(0)
	global_store_dwordx2 v[46:47], v[44:45], off offset:32
	v_pk_mul_f32 v[44:45], v[50:51], v[144:145] op_sel_hi:[1,0]
	v_pk_mul_f32 v[46:47], v[48:49], v[144:145] op_sel_hi:[1,0]
	v_mul_f32_e32 v50, 0xbfb8aa3b, v44
	v_mul_f32_e32 v48, 0xbfb8aa3b, v46
	v_mul_f32_e32 v49, 0xbfb8aa3b, v47
	v_mul_f32_e32 v51, 0xbfb8aa3b, v45
	v_exp_f32_e32 v48, v48
	v_exp_f32_e32 v49, v49
	v_exp_f32_e32 v50, v50
	v_exp_f32_e32 v51, v51
	v_add_f32_e32 v48, 1.0, v48
	v_add_f32_e32 v49, 1.0, v49
	v_add_f32_e32 v50, 1.0, v50
	v_add_f32_e32 v51, 1.0, v51
	v_rcp_f32_e32 v48, v48
	v_rcp_f32_e32 v49, v49
	v_rcp_f32_e32 v50, v50
	v_rcp_f32_e32 v51, v51
	v_pk_mul_f32 v[38:39], v[38:39], v[144:145] op_sel_hi:[1,0]
	v_pk_mul_f32 v[36:37], v[36:37], v[144:145] op_sel_hi:[1,0]
	v_pk_mul_f32 v[46:47], v[46:47], v[48:49]
	v_pk_mul_f32 v[44:45], v[44:45], v[50:51]
	v_pk_mul_f32 v[36:37], v[36:37], v[46:47]
	v_pk_mul_f32 v[38:39], v[38:39], v[44:45]
	v_cvt_pk_bf16_f32 v36, v36, v37
	v_cvt_pk_bf16_f32 v37, v38, v39
	v_pk_mul_f32 v[38:39], v[42:43], v[144:145] op_sel_hi:[1,0]
	v_pk_mul_f32 v[40:41], v[40:41], v[144:145] op_sel_hi:[1,0]
	v_mul_f32_e32 v44, 0xbfb8aa3b, v38
	v_mul_f32_e32 v42, 0xbfb8aa3b, v40
	v_mul_f32_e32 v43, 0xbfb8aa3b, v41
	v_mul_f32_e32 v45, 0xbfb8aa3b, v39
	v_exp_f32_e32 v42, v42
	v_exp_f32_e32 v43, v43
	v_exp_f32_e32 v44, v44
	v_exp_f32_e32 v45, v45
	v_add_f32_e32 v42, 1.0, v42
	v_add_f32_e32 v43, 1.0, v43
	v_add_f32_e32 v44, 1.0, v44
	v_add_f32_e32 v45, 1.0, v45
	v_rcp_f32_e32 v42, v42
	v_rcp_f32_e32 v43, v43
	v_rcp_f32_e32 v44, v44
	v_rcp_f32_e32 v45, v45
	v_pk_mul_f32 v[30:31], v[30:31], v[144:145] op_sel_hi:[1,0]
	v_pk_mul_f32 v[28:29], v[28:29], v[144:145] op_sel_hi:[1,0]
	v_pk_mul_f32 v[40:41], v[40:41], v[42:43]
	v_pk_mul_f32 v[38:39], v[38:39], v[44:45]
	v_pk_mul_f32 v[28:29], v[28:29], v[40:41]
	v_pk_mul_f32 v[30:31], v[30:31], v[38:39]
	ds_bpermute_b32 v36, v149, v36
	ds_bpermute_b32 v37, v149, v37
	v_cvt_pk_bf16_f32 v28, v28, v29
	v_cvt_pk_bf16_f32 v29, v30, v31
	ds_bpermute_b32 v28, v149, v28
	ds_bpermute_b32 v29, v149, v29
	v_add_u32_e32 v52, 0x90, v151
	v_mad_i64_i32 v[30:31], s[22:23], v52, s47, v[136:137]
	v_lshl_add_u64 v[30:31], v[30:31], 0, v[140:141]
	s_waitcnt lgkmcnt(2)
	global_store_dwordx2 v[30:31], v[36:37], off
	s_waitcnt lgkmcnt(0)
	global_store_dwordx2 v[30:31], v[28:29], off offset:32
	v_pk_mul_f32 v[28:29], v[34:35], v[142:143] op_sel_hi:[1,0]
	v_pk_mul_f32 v[30:31], v[32:33], v[142:143] op_sel_hi:[1,0]
	v_mul_f32_e32 v34, 0xbfb8aa3b, v28
	v_mul_f32_e32 v32, 0xbfb8aa3b, v30
	v_mul_f32_e32 v33, 0xbfb8aa3b, v31
	v_mul_f32_e32 v35, 0xbfb8aa3b, v29
	v_exp_f32_e32 v32, v32
	v_exp_f32_e32 v33, v33
	v_exp_f32_e32 v34, v34
	v_exp_f32_e32 v35, v35
	v_add_f32_e32 v32, 1.0, v32
	v_add_f32_e32 v33, 1.0, v33
	v_add_f32_e32 v34, 1.0, v34
	v_add_f32_e32 v35, 1.0, v35
	v_rcp_f32_e32 v32, v32
	v_rcp_f32_e32 v33, v33
	v_rcp_f32_e32 v34, v34
	v_rcp_f32_e32 v35, v35
	v_pk_mul_f32 v[22:23], v[22:23], v[142:143] op_sel_hi:[1,0]
	v_pk_mul_f32 v[20:21], v[20:21], v[142:143] op_sel_hi:[1,0]
	v_pk_mul_f32 v[30:31], v[30:31], v[32:33]
	v_pk_mul_f32 v[28:29], v[28:29], v[34:35]
	v_pk_mul_f32 v[20:21], v[20:21], v[30:31]
	v_pk_mul_f32 v[22:23], v[22:23], v[28:29]
	v_cvt_pk_bf16_f32 v20, v20, v21
	v_cvt_pk_bf16_f32 v21, v22, v23
	v_pk_mul_f32 v[22:23], v[26:27], v[142:143] op_sel_hi:[1,0]
	v_pk_mul_f32 v[24:25], v[24:25], v[142:143] op_sel_hi:[1,0]
	v_mul_f32_e32 v28, 0xbfb8aa3b, v22
	v_mul_f32_e32 v26, 0xbfb8aa3b, v24
	v_mul_f32_e32 v27, 0xbfb8aa3b, v25
	v_mul_f32_e32 v29, 0xbfb8aa3b, v23
	v_exp_f32_e32 v26, v26
	v_exp_f32_e32 v27, v27
	v_exp_f32_e32 v28, v28
	v_exp_f32_e32 v29, v29
	v_add_f32_e32 v26, 1.0, v26
	v_add_f32_e32 v27, 1.0, v27
	v_add_f32_e32 v28, 1.0, v28
	v_add_f32_e32 v29, 1.0, v29
	v_rcp_f32_e32 v26, v26
	v_rcp_f32_e32 v27, v27
	v_rcp_f32_e32 v28, v28
	v_rcp_f32_e32 v29, v29
	v_pk_mul_f32 v[14:15], v[14:15], v[142:143] op_sel_hi:[1,0]
	v_pk_mul_f32 v[12:13], v[12:13], v[142:143] op_sel_hi:[1,0]
	v_pk_mul_f32 v[24:25], v[24:25], v[26:27]
	v_pk_mul_f32 v[22:23], v[22:23], v[28:29]
	v_pk_mul_f32 v[12:13], v[12:13], v[24:25]
	v_pk_mul_f32 v[14:15], v[14:15], v[22:23]
	ds_bpermute_b32 v20, v149, v20
	ds_bpermute_b32 v21, v149, v21
	v_cvt_pk_bf16_f32 v12, v12, v13
	v_cvt_pk_bf16_f32 v13, v14, v15
	ds_bpermute_b32 v12, v149, v12
	ds_bpermute_b32 v13, v149, v13
	v_add_u32_e32 v36, 0xa0, v151
	v_mad_i64_i32 v[14:15], s[22:23], v36, s47, v[136:137]
	v_lshl_add_u64 v[14:15], v[14:15], 0, v[140:141]
	s_waitcnt lgkmcnt(2)
	global_store_dwordx2 v[14:15], v[20:21], off
	s_waitcnt lgkmcnt(0)
	global_store_dwordx2 v[14:15], v[12:13], off offset:32
	v_pk_mul_f32 v[12:13], v[18:19], v[138:139] op_sel_hi:[1,0]
	v_pk_mul_f32 v[14:15], v[16:17], v[138:139] op_sel_hi:[1,0]
	v_mul_f32_e32 v18, 0xbfb8aa3b, v12
	v_mul_f32_e32 v16, 0xbfb8aa3b, v14
	v_mul_f32_e32 v17, 0xbfb8aa3b, v15
	v_mul_f32_e32 v19, 0xbfb8aa3b, v13
	v_exp_f32_e32 v16, v16
	v_exp_f32_e32 v17, v17
	v_exp_f32_e32 v18, v18
	v_exp_f32_e32 v19, v19
	v_add_f32_e32 v16, 1.0, v16
	v_add_f32_e32 v17, 1.0, v17
	v_add_f32_e32 v18, 1.0, v18
	v_add_f32_e32 v19, 1.0, v19
	v_rcp_f32_e32 v16, v16
	v_rcp_f32_e32 v17, v17
	v_rcp_f32_e32 v18, v18
	v_rcp_f32_e32 v19, v19
	v_pk_mul_f32 v[6:7], v[6:7], v[138:139] op_sel_hi:[1,0]
	v_pk_mul_f32 v[4:5], v[4:5], v[138:139] op_sel_hi:[1,0]
	v_pk_mul_f32 v[14:15], v[14:15], v[16:17]
	v_pk_mul_f32 v[12:13], v[12:13], v[18:19]
	v_pk_mul_f32 v[4:5], v[4:5], v[14:15]
	v_pk_mul_f32 v[6:7], v[6:7], v[12:13]
	v_cvt_pk_bf16_f32 v4, v4, v5
	v_cvt_pk_bf16_f32 v5, v6, v7
	v_pk_mul_f32 v[6:7], v[10:11], v[138:139] op_sel_hi:[1,0]
	v_pk_mul_f32 v[8:9], v[8:9], v[138:139] op_sel_hi:[1,0]
	v_mul_f32_e32 v12, 0xbfb8aa3b, v6
	v_mul_f32_e32 v10, 0xbfb8aa3b, v8
	v_mul_f32_e32 v11, 0xbfb8aa3b, v9
	v_mul_f32_e32 v13, 0xbfb8aa3b, v7
	v_exp_f32_e32 v10, v10
	v_exp_f32_e32 v11, v11
	v_exp_f32_e32 v12, v12
	v_exp_f32_e32 v13, v13
	v_add_f32_e32 v10, 1.0, v10
	v_add_f32_e32 v11, 1.0, v11
	v_add_f32_e32 v12, 1.0, v12
	v_add_f32_e32 v13, 1.0, v13
	v_rcp_f32_e32 v10, v10
	v_rcp_f32_e32 v11, v11
	v_rcp_f32_e32 v12, v12
	v_rcp_f32_e32 v13, v13
	v_pk_mul_f32 v[2:3], v[2:3], v[138:139] op_sel_hi:[1,0]
	v_pk_mul_f32 v[0:1], v[0:1], v[138:139] op_sel_hi:[1,0]
	v_pk_mul_f32 v[8:9], v[8:9], v[10:11]
	v_pk_mul_f32 v[6:7], v[6:7], v[12:13]
	v_pk_mul_f32 v[0:1], v[0:1], v[8:9]
	v_pk_mul_f32 v[2:3], v[2:3], v[6:7]
	ds_bpermute_b32 v4, v149, v4
	ds_bpermute_b32 v5, v149, v5
	v_cvt_pk_bf16_f32 v0, v0, v1
	v_cvt_pk_bf16_f32 v1, v2, v3
	ds_bpermute_b32 v0, v149, v0
	ds_bpermute_b32 v1, v149, v1
	v_add_u32_e32 v20, 0xb0, v151
	v_mad_i64_i32 v[2:3], s[22:23], v20, s47, v[136:137]
	v_lshl_add_u64 v[2:3], v[2:3], 0, v[140:141]
	s_mov_b64 s[22:23], s[16:17]
	s_waitcnt lgkmcnt(2)
	global_store_dwordx2 v[2:3], v[4:5], off
	s_waitcnt lgkmcnt(0)
	global_store_dwordx2 v[2:3], v[0:1], off offset:32
	s_cbranch_vccz .LBB0_1164
	s_waitcnt vmcnt(0)
	s_cmpk_gt_u32 s28, 0xff
	s_cbranch_scc1 .LBB0_1171
	s_barrier

.LBB0_1258:
	ds_read_b128 v[128:131], v159
	ds_read_b128 v[132:135], v159 offset:1024
	ds_read_b128 v[136:139], v159 offset:2048
	ds_read_b128 v[150:153], v159 offset:3072
	s_add_i32 s54, s18, 2
	s_add_u32 s19, s16, 0xffea0080
	s_addc_u32 s20, s17, -1
	s_cmp_eq_u32 s13, s18
	s_cselect_b32 s18, s4, s52
	s_cselect_b32 s21, s15, s20
	s_cselect_b32 s20, s14, s19
	s_cselect_b32 s19, s5, s53
	v_lshl_add_u64 v[166:167], s[16:17], 0, v[146:147]
	s_add_i32 m0, s26, 0xc000
	ds_read_b128 v[154:157], v160
	ds_read_b128 v[162:165], v160 offset:1024
	ds_read_b128 v[172:175], v160 offset:2048
	ds_read_b128 v[176:179], v160 offset:3072
	ds_read_b128 v[180:183], v160 offset:4096
	ds_read_b128 v[184:187], v160 offset:5120
	ds_read_b128 v[188:191], v160 offset:6144
	ds_read_b128 v[192:195], v160 offset:7168
	global_load_lds_dwordx4 v[166:167], off
	v_lshl_add_u64 v[166:167], s[16:17], 0, v[148:149]
	s_add_i32 m0, s26, 0xe000
	s_nop 0
	global_load_lds_dwordx4 v[166:167], off
	s_waitcnt lgkmcnt(8)
	s_barrier
	s_waitcnt lgkmcnt(0)

	s_waitcnt lgkmcnt(0)
	v_mfma_f32_16x16x32_bf16 v[124:127], v[128:131], v[154:157], v[124:127]
	v_mfma_f32_16x16x32_bf16 v[120:123], v[136:139], v[154:157], v[120:123]
	v_mfma_f32_16x16x32_bf16 v[116:119], v[128:131], v[172:175], v[116:119]
	v_mfma_f32_16x16x32_bf16 v[104:107], v[136:139], v[172:175], v[104:107]
	v_mfma_f32_16x16x32_bf16 v[96:99], v[128:131], v[180:183], v[96:99]
	v_mfma_f32_16x16x32_bf16 v[88:91], v[136:139], v[180:183], v[88:91]
	v_mfma_f32_16x16x32_bf16 v[80:83], v[128:131], v[188:191], v[80:83]
	v_mfma_f32_16x16x32_bf16 v[72:75], v[136:139], v[188:191], v[72:75]
	v_mfma_f32_16x16x32_bf16 v[124:127], v[132:135], v[162:165], v[124:127]
	v_mfma_f32_16x16x32_bf16 v[120:123], v[150:153], v[162:165], v[120:123]
	v_mfma_f32_16x16x32_bf16 v[116:119], v[132:135], v[176:179], v[116:119]
	v_mfma_f32_16x16x32_bf16 v[104:107], v[150:153], v[176:179], v[104:107]
	v_mfma_f32_16x16x32_bf16 v[96:99], v[132:135], v[184:187], v[96:99]
	v_mfma_f32_16x16x32_bf16 v[88:91], v[150:153], v[184:187], v[88:91]
	v_mfma_f32_16x16x32_bf16 v[80:83], v[132:135], v[192:195], v[80:83]
	v_mfma_f32_16x16x32_bf16 v[72:75], v[150:153], v[192:195], v[72:75]

	s_barrier
	s_add_i32 s55, s35, s25
	v_lshl_add_u64 v[166:167], s[18:19], 0, v[140:141]
	s_mov_b32 m0, s55
	ds_read_b128 v[196:199], v161
	ds_read_b128 v[200:203], v161 offset:1024
	ds_read_b128 v[204:207], v161 offset:2048
	ds_read_b128 v[212:215], v161 offset:3072
	global_load_lds_dwordx4 v[166:167], off
	v_lshl_add_u64 v[208:209], s[18:19], 0, v[142:143]
	s_add_i32 m0, s55, 0x2000
	s_nop 0
	global_load_lds_dwordx4 v[208:209], off
	s_barrier
	s_waitcnt lgkmcnt(0)

	s_waitcnt lgkmcnt(0)
	v_mfma_f32_16x16x32_bf16 v[112:115], v[196:199], v[154:157], v[112:115]
	v_mfma_f32_16x16x32_bf16 v[108:111], v[204:207], v[154:157], v[108:111]
	v_mfma_f32_16x16x32_bf16 v[100:103], v[196:199], v[172:175], v[100:103]
	v_mfma_f32_16x16x32_bf16 v[92:95], v[204:207], v[172:175], v[92:95]
	v_mfma_f32_16x16x32_bf16 v[84:87], v[196:199], v[180:183], v[84:87]
	v_mfma_f32_16x16x32_bf16 v[76:79], v[204:207], v[180:183], v[76:79]
	v_mfma_f32_16x16x32_bf16 v[68:71], v[196:199], v[188:191], v[68:71]
	v_mfma_f32_16x16x32_bf16 v[64:67], v[204:207], v[188:191], v[64:67]
	v_mfma_f32_16x16x32_bf16 v[112:115], v[200:203], v[162:165], v[112:115]
	v_mfma_f32_16x16x32_bf16 v[108:111], v[212:215], v[162:165], v[108:111]
	v_mfma_f32_16x16x32_bf16 v[100:103], v[200:203], v[176:179], v[100:103]
	v_mfma_f32_16x16x32_bf16 v[92:95], v[212:215], v[176:179], v[92:95]
	v_mfma_f32_16x16x32_bf16 v[84:87], v[200:203], v[184:187], v[84:87]
	v_mfma_f32_16x16x32_bf16 v[76:79], v[212:215], v[184:187], v[76:79]
	v_mfma_f32_16x16x32_bf16 v[68:71], v[200:203], v[192:195], v[68:71]
	v_mfma_f32_16x16x32_bf16 v[64:67], v[212:215], v[192:195], v[64:67]

	s_mov_b32 m0, s26
	v_lshl_add_u64 v[216:217], s[20:21], 0, v[140:141]
	s_barrier
	ds_read_b128 v[154:157], v160 offset:16384
	ds_read_b128 v[162:165], v160 offset:17408
	ds_read_b128 v[172:175], v160 offset:18432
	ds_read_b128 v[176:179], v160 offset:19456
	ds_read_b128 v[180:183], v160 offset:20480
	ds_read_b128 v[184:187], v160 offset:21504
	ds_read_b128 v[188:191], v160 offset:22528
	ds_read_b128 v[192:195], v160 offset:23552
	global_load_lds_dwordx4 v[216:217], off
	v_lshl_add_u64 v[218:219], s[20:21], 0, v[142:143]
	s_mov_b32 m0, s27
	s_nop 0
	global_load_lds_dwordx4 v[218:219], off
	s_barrier
	s_waitcnt lgkmcnt(0)

	s_waitcnt lgkmcnt(0)
	v_mfma_f32_16x16x32_bf16 v[60:63], v[128:131], v[154:157], v[60:63]
	v_mfma_f32_16x16x32_bf16 v[56:59], v[136:139], v[154:157], v[56:59]
	v_mfma_f32_16x16x32_bf16 v[52:55], v[128:131], v[172:175], v[52:55]
	v_mfma_f32_16x16x32_bf16 v[40:43], v[136:139], v[172:175], v[40:43]
	v_mfma_f32_16x16x32_bf16 v[36:39], v[128:131], v[180:183], v[36:39]
	v_mfma_f32_16x16x32_bf16 v[24:27], v[136:139], v[180:183], v[24:27]
	v_mfma_f32_16x16x32_bf16 v[20:23], v[128:131], v[188:191], v[20:23]
	v_mfma_f32_16x16x32_bf16 v[8:11], v[136:139], v[188:191], v[8:11]
	v_mfma_f32_16x16x32_bf16 v[60:63], v[132:135], v[162:165], v[60:63]
	v_mfma_f32_16x16x32_bf16 v[56:59], v[150:153], v[162:165], v[56:59]
	v_mfma_f32_16x16x32_bf16 v[52:55], v[132:135], v[176:179], v[52:55]
	v_mfma_f32_16x16x32_bf16 v[40:43], v[150:153], v[176:179], v[40:43]
	v_mfma_f32_16x16x32_bf16 v[36:39], v[132:135], v[184:187], v[36:39]
	v_mfma_f32_16x16x32_bf16 v[24:27], v[150:153], v[184:187], v[24:27]
	v_mfma_f32_16x16x32_bf16 v[20:23], v[132:135], v[192:195], v[20:23]
	v_mfma_f32_16x16x32_bf16 v[8:11], v[150:153], v[192:195], v[8:11]

	s_barrier
	s_add_u32 s56, s18, 0x160000
	s_addc_u32 s57, s19, 0
	s_add_i32 s55, s36, s25
	v_lshl_add_u64 v[128:129], s[56:57], 0, v[140:141]
	s_mov_b32 m0, s55
	s_nop 0
	global_load_lds_dwordx4 v[128:129], off
	v_lshl_add_u64 v[128:129], s[56:57], 0, v[142:143]
	s_add_i32 m0, s55, 0x2000
	s_nop 0
	global_load_lds_dwordx4 v[128:129], off
	s_waitcnt vmcnt(6)
	s_barrier

	v_mfma_f32_16x16x32_bf16 v[48:51], v[196:199], v[154:157], v[48:51]
	v_mfma_f32_16x16x32_bf16 v[44:47], v[204:207], v[154:157], v[44:47]
	v_mfma_f32_16x16x32_bf16 v[32:35], v[196:199], v[172:175], v[32:35]
	v_mfma_f32_16x16x32_bf16 v[28:31], v[204:207], v[172:175], v[28:31]
	v_mfma_f32_16x16x32_bf16 v[16:19], v[196:199], v[180:183], v[16:19]
	v_mfma_f32_16x16x32_bf16 v[12:15], v[204:207], v[180:183], v[12:15]
	v_mfma_f32_16x16x32_bf16 v[4:7], v[196:199], v[188:191], v[4:7]
	v_mfma_f32_16x16x32_bf16 v[0:3], v[204:207], v[188:191], v[0:3]
	v_mfma_f32_16x16x32_bf16 v[48:51], v[200:203], v[162:165], v[48:51]
	v_mfma_f32_16x16x32_bf16 v[44:47], v[212:215], v[162:165], v[44:47]
	v_mfma_f32_16x16x32_bf16 v[32:35], v[200:203], v[176:179], v[32:35]
	v_mfma_f32_16x16x32_bf16 v[28:31], v[212:215], v[176:179], v[28:31]
	v_mfma_f32_16x16x32_bf16 v[16:19], v[200:203], v[184:187], v[16:19]
	v_mfma_f32_16x16x32_bf16 v[12:15], v[212:215], v[184:187], v[12:15]
	v_mfma_f32_16x16x32_bf16 v[4:7], v[200:203], v[192:195], v[4:7]
	v_mfma_f32_16x16x32_bf16 v[0:3], v[212:215], v[192:195], v[0:3]

	s_add_i32 s55, 0, 0x18000
	v_add_u32_e32 v144, s55, v158
	s_barrier
	ds_read_b128 v[128:131], v144
	ds_read_b128 v[132:135], v144 offset:1024
	ds_read_b128 v[136:139], v144 offset:2048
	ds_read_b128 v[150:153], v144 offset:3072
	s_add_u32 s20, s20, 0x160000
	s_addc_u32 s21, s21, 0
	s_mov_b32 m0, s28
	v_lshl_add_u64 v[196:197], s[20:21], 0, v[140:141]
	ds_read_b128 v[154:157], v160 offset:32768
	ds_read_b128 v[162:165], v160 offset:33792
	ds_read_b128 v[172:175], v160 offset:34816
	ds_read_b128 v[176:179], v160 offset:35840
	ds_read_b128 v[180:183], v160 offset:36864
	ds_read_b128 v[184:187], v160 offset:37888
	ds_read_b128 v[188:191], v160 offset:38912
	ds_read_b128 v[192:195], v160 offset:39936
	global_load_lds_dwordx4 v[196:197], off
	v_lshl_add_u64 v[196:197], s[20:21], 0, v[142:143]
	s_mov_b32 m0, s29
	s_nop 0
	global_load_lds_dwordx4 v[196:197], off
	s_waitcnt lgkmcnt(8)
	s_barrier
	s_waitcnt lgkmcnt(0)

	s_waitcnt lgkmcnt(0)
	v_mfma_f32_16x16x32_bf16 v[124:127], v[128:131], v[154:157], v[124:127]
	v_mfma_f32_16x16x32_bf16 v[120:123], v[136:139], v[154:157], v[120:123]
	v_mfma_f32_16x16x32_bf16 v[116:119], v[128:131], v[172:175], v[116:119]
	v_mfma_f32_16x16x32_bf16 v[104:107], v[136:139], v[172:175], v[104:107]
	v_mfma_f32_16x16x32_bf16 v[96:99], v[128:131], v[180:183], v[96:99]
	v_mfma_f32_16x16x32_bf16 v[88:91], v[136:139], v[180:183], v[88:91]
	v_mfma_f32_16x16x32_bf16 v[80:83], v[128:131], v[188:191], v[80:83]
	v_mfma_f32_16x16x32_bf16 v[72:75], v[136:139], v[188:191], v[72:75]
	v_mfma_f32_16x16x32_bf16 v[124:127], v[132:135], v[162:165], v[124:127]
	v_mfma_f32_16x16x32_bf16 v[120:123], v[150:153], v[162:165], v[120:123]
	v_mfma_f32_16x16x32_bf16 v[116:119], v[132:135], v[176:179], v[116:119]
	v_mfma_f32_16x16x32_bf16 v[104:107], v[150:153], v[176:179], v[104:107]
	v_mfma_f32_16x16x32_bf16 v[96:99], v[132:135], v[184:187], v[96:99]
	v_mfma_f32_16x16x32_bf16 v[88:91], v[150:153], v[184:187], v[88:91]
	v_mfma_f32_16x16x32_bf16 v[80:83], v[132:135], v[192:195], v[80:83]
	v_mfma_f32_16x16x32_bf16 v[72:75], v[150:153], v[192:195], v[72:75]

	s_barrier
	s_add_i32 s20, 0, 0x1c000
	s_add_i32 s21, s55, s25
	v_add_u32_e32 v144, s20, v158
	v_lshl_add_u64 v[166:167], v[166:167], 0, s[6:7]
	s_mov_b32 m0, s21
	ds_read_b128 v[196:199], v144
	ds_read_b128 v[200:203], v144 offset:1024
	ds_read_b128 v[204:207], v144 offset:2048
	ds_read_b128 v[212:215], v144 offset:3072
	global_load_lds_dwordx4 v[166:167], off
	v_lshl_add_u64 v[166:167], v[208:209], 0, s[6:7]
	s_add_i32 m0, s21, 0x2000
	s_nop 0
	global_load_lds_dwordx4 v[166:167], off
	s_barrier
	s_waitcnt lgkmcnt(0)

	s_waitcnt lgkmcnt(0)
	v_mfma_f32_16x16x32_bf16 v[112:115], v[196:199], v[154:157], v[112:115]
	v_mfma_f32_16x16x32_bf16 v[108:111], v[204:207], v[154:157], v[108:111]
	v_mfma_f32_16x16x32_bf16 v[100:103], v[196:199], v[172:175], v[100:103]
	v_mfma_f32_16x16x32_bf16 v[92:95], v[204:207], v[172:175], v[92:95]
	v_mfma_f32_16x16x32_bf16 v[84:87], v[196:199], v[180:183], v[84:87]
	v_mfma_f32_16x16x32_bf16 v[76:79], v[204:207], v[180:183], v[76:79]
	v_mfma_f32_16x16x32_bf16 v[68:71], v[196:199], v[188:191], v[68:71]
	v_mfma_f32_16x16x32_bf16 v[64:67], v[204:207], v[188:191], v[64:67]
	v_mfma_f32_16x16x32_bf16 v[112:115], v[200:203], v[162:165], v[112:115]
	v_mfma_f32_16x16x32_bf16 v[108:111], v[212:215], v[162:165], v[108:111]
	v_mfma_f32_16x16x32_bf16 v[100:103], v[200:203], v[176:179], v[100:103]
	v_mfma_f32_16x16x32_bf16 v[92:95], v[212:215], v[176:179], v[92:95]
	v_mfma_f32_16x16x32_bf16 v[84:87], v[200:203], v[184:187], v[84:87]
	v_mfma_f32_16x16x32_bf16 v[76:79], v[212:215], v[184:187], v[76:79]
	v_mfma_f32_16x16x32_bf16 v[68:71], v[200:203], v[192:195], v[68:71]
	v_mfma_f32_16x16x32_bf16 v[64:67], v[212:215], v[192:195], v[64:67]

	s_mov_b32 m0, s33
	v_lshl_add_u64 v[166:167], v[216:217], 0, s[6:7]
	s_barrier
	ds_read_b128 v[154:157], v160 offset:49152
	ds_read_b128 v[162:165], v160 offset:50176
	ds_read_b128 v[172:175], v160 offset:51200
	ds_read_b128 v[176:179], v160 offset:52224
	ds_read_b128 v[180:183], v160 offset:53248
	ds_read_b128 v[184:187], v160 offset:54272
	ds_read_b128 v[188:191], v160 offset:55296
	ds_read_b128 v[192:195], v160 offset:56320
	global_load_lds_dwordx4 v[166:167], off
	v_lshl_add_u64 v[166:167], v[218:219], 0, s[6:7]
	s_mov_b32 m0, s34
	s_nop 0
	global_load_lds_dwordx4 v[166:167], off
	s_barrier
	s_waitcnt lgkmcnt(0)

	s_waitcnt lgkmcnt(0)
	v_mfma_f32_16x16x32_bf16 v[60:63], v[128:131], v[154:157], v[60:63]
	v_mfma_f32_16x16x32_bf16 v[56:59], v[136:139], v[154:157], v[56:59]
	v_mfma_f32_16x16x32_bf16 v[52:55], v[128:131], v[172:175], v[52:55]
	v_mfma_f32_16x16x32_bf16 v[40:43], v[136:139], v[172:175], v[40:43]
	v_mfma_f32_16x16x32_bf16 v[36:39], v[128:131], v[180:183], v[36:39]
	v_mfma_f32_16x16x32_bf16 v[24:27], v[136:139], v[180:183], v[24:27]
	v_mfma_f32_16x16x32_bf16 v[20:23], v[128:131], v[188:191], v[20:23]
	v_mfma_f32_16x16x32_bf16 v[8:11], v[136:139], v[188:191], v[8:11]
	v_mfma_f32_16x16x32_bf16 v[60:63], v[132:135], v[162:165], v[60:63]
	v_mfma_f32_16x16x32_bf16 v[56:59], v[150:153], v[162:165], v[56:59]
	v_mfma_f32_16x16x32_bf16 v[52:55], v[132:135], v[176:179], v[52:55]
	v_mfma_f32_16x16x32_bf16 v[40:43], v[150:153], v[176:179], v[40:43]
	v_mfma_f32_16x16x32_bf16 v[36:39], v[132:135], v[184:187], v[36:39]
	v_mfma_f32_16x16x32_bf16 v[24:27], v[150:153], v[184:187], v[24:27]
	v_mfma_f32_16x16x32_bf16 v[20:23], v[132:135], v[192:195], v[20:23]
	v_mfma_f32_16x16x32_bf16 v[8:11], v[150:153], v[192:195], v[8:11]

	s_barrier
	s_add_u32 s18, s18, 0x160080
	s_addc_u32 s19, s19, 0
	s_add_i32 s20, s20, s25
	v_lshl_add_u64 v[128:129], s[18:19], 0, v[140:141]
	s_mov_b32 m0, s20
	s_nop 0
	global_load_lds_dwordx4 v[128:129], off
	v_lshl_add_u64 v[128:129], s[18:19], 0, v[142:143]
	s_add_i32 m0, s20, 0x2000
	s_nop 0
	global_load_lds_dwordx4 v[128:129], off
	s_waitcnt vmcnt(6)
	s_barrier

	v_mfma_f32_16x16x32_bf16 v[48:51], v[196:199], v[154:157], v[48:51]
	v_mfma_f32_16x16x32_bf16 v[44:47], v[204:207], v[154:157], v[44:47]
	v_mfma_f32_16x16x32_bf16 v[32:35], v[196:199], v[172:175], v[32:35]
	v_mfma_f32_16x16x32_bf16 v[28:31], v[204:207], v[172:175], v[28:31]
	v_mfma_f32_16x16x32_bf16 v[16:19], v[196:199], v[180:183], v[16:19]
	v_mfma_f32_16x16x32_bf16 v[12:15], v[204:207], v[180:183], v[12:15]
	v_mfma_f32_16x16x32_bf16 v[4:7], v[196:199], v[188:191], v[4:7]
	v_mfma_f32_16x16x32_bf16 v[0:3], v[204:207], v[188:191], v[0:3]
	v_mfma_f32_16x16x32_bf16 v[48:51], v[200:203], v[162:165], v[48:51]
	v_mfma_f32_16x16x32_bf16 v[44:47], v[212:215], v[162:165], v[44:47]
	v_mfma_f32_16x16x32_bf16 v[32:35], v[200:203], v[176:179], v[32:35]
	v_mfma_f32_16x16x32_bf16 v[28:31], v[212:215], v[176:179], v[28:31]
	v_mfma_f32_16x16x32_bf16 v[16:19], v[200:203], v[184:187], v[16:19]
	v_mfma_f32_16x16x32_bf16 v[12:15], v[212:215], v[184:187], v[12:15]
	v_mfma_f32_16x16x32_bf16 v[4:7], v[200:203], v[192:195], v[4:7]
	v_mfma_f32_16x16x32_bf16 v[0:3], v[212:215], v[192:195], v[0:3]

	s_add_u32 s16, s16, 0x100
	s_addc_u32 s17, s17, 0
	s_add_u32 s52, s52, 0x100
	s_addc_u32 s53, s53, 0
	s_cmp_ge_i32 s54, s51
	s_mov_b32 s18, s54
	s_barrier
	s_cbranch_scc0 .LBB0_1258
	v_mov_b32_e32 v128, v210
	v_mov_b32_e32 v129, v169
	s_mov_b64 s[16:17], -1
	v_lshl_add_u32 v128, v128, 4, v129
	v_ashrrev_i32_e32 v150, 2, v128
	v_and_b32_e32 v129, 3, v129
	v_and_b32_e32 v128, -4, v128
	v_lshl_add_u32 v162, v129, 6, v128
	s_cmp_lt_i32 s2, 0
	v_lshlrev_b32_e32 v144, 4, v129
	s_cbranch_scc0 .LBB0_1261
	s_lshl_b32 s13, s50, 8
	s_add_i32 s13, s13, s30
	v_add_u32_e32 v128, s13, v150
	v_ashrrev_i32_e32 v129, 31, v128
	v_readlane_b32 s52, v254, 22
	v_lshlrev_b64 v[128:129], 13, v[128:129]
	v_readlane_b32 s66, v254, 36
	v_readlane_b32 s67, v254, 37
	s_lshl_b32 s16, s49, 8
	s_ashr_i32 s17, s16, 31
	v_lshl_add_u64 v[128:129], s[66:67], 0, v[128:129]
	v_lshl_add_u64 v[128:129], s[16:17], 2, v[128:129]
	s_lshl_b32 s16, s31, 2
	s_mov_b32 s17, s3
	v_lshl_add_u64 v[128:129], v[128:129], 0, s[16:17]
	v_lshl_add_u64 v[152:153], v[128:129], 0, v[144:145]
	global_load_dwordx4 v[164:167], v[152:153], off
	global_load_dwordx4 v[172:175], v[152:153], off offset:64
	global_load_dwordx4 v[176:179], v[152:153], off offset:512
	global_load_dwordx4 v[180:183], v[152:153], off offset:576
	v_add_co_u32_e32 v136, vcc, s37, v152
	ds_bpermute_b32 v138, v162, v124
	s_nop 0
	v_addc_co_u32_e32 v137, vcc, 0, v153, vcc
	global_load_dwordx4 v[184:187], v[136:137], off
	global_load_dwordx4 v[188:191], v[136:137], off offset:64
	global_load_dwordx4 v[192:195], v[136:137], off offset:512
	global_load_dwordx4 v[132:135], v[136:137], off offset:576
	v_add_co_u32_e32 v208, vcc, s38, v152
	ds_bpermute_b32 v139, v162, v125
	s_nop 0
	v_addc_co_u32_e32 v209, vcc, 0, v153, vcc
	global_load_dwordx4 v[196:199], v[208:209], off
	global_load_dwordx4 v[200:203], v[208:209], off offset:64
	global_load_dwordx4 v[204:207], v[208:209], off offset:512
	global_load_dwordx4 v[212:215], v[208:209], off offset:576
	v_add_co_u32_e32 v154, vcc, s39, v152
	ds_bpermute_b32 v156, v162, v126
	s_nop 0
	v_addc_co_u32_e32 v155, vcc, 0, v153, vcc
	global_load_dwordx4 v[216:219], v[154:155], off
	global_load_dwordx4 v[220:223], v[154:155], off offset:64
	global_load_dwordx4 v[224:227], v[154:155], off offset:512
	global_load_dwordx4 v[128:131], v[154:155], off offset:576
	ds_bpermute_b32 v157, v162, v127
	ds_bpermute_b32 v228, v162, v120
	ds_bpermute_b32 v229, v162, v121
	ds_bpermute_b32 v230, v162, v122
	ds_bpermute_b32 v231, v162, v123
	ds_bpermute_b32 v232, v162, v112
	ds_bpermute_b32 v233, v162, v113
	ds_bpermute_b32 v234, v162, v114
	ds_bpermute_b32 v235, v162, v115
	ds_bpermute_b32 v236, v162, v108
	ds_bpermute_b32 v237, v162, v109
	ds_bpermute_b32 v238, v162, v110
	ds_bpermute_b32 v239, v162, v111
	ds_bpermute_b32 v240, v162, v116
	ds_bpermute_b32 v241, v162, v117
	ds_bpermute_b32 v242, v162, v118
	ds_bpermute_b32 v243, v162, v119
	ds_bpermute_b32 v244, v162, v104
	ds_bpermute_b32 v245, v162, v105
	ds_bpermute_b32 v246, v162, v106
	ds_bpermute_b32 v247, v162, v107
	ds_bpermute_b32 v248, v162, v100
	ds_bpermute_b32 v249, v162, v101
	ds_bpermute_b32 v250, v162, v102
	ds_bpermute_b32 v251, v162, v103
	ds_bpermute_b32 v252, v162, v94
	ds_bpermute_b32 v253, v162, v95
	v_readlane_b32 s53, v254, 23
	v_readlane_b32 s54, v254, 24
	v_readlane_b32 s55, v254, 25
	v_readlane_b32 s56, v254, 26
	v_readlane_b32 s57, v254, 27
	v_readlane_b32 s58, v254, 28
	v_readlane_b32 s59, v254, 29
	v_readlane_b32 s60, v254, 30
	v_readlane_b32 s61, v254, 31
	v_readlane_b32 s62, v254, 32
	v_readlane_b32 s63, v254, 33
	v_readlane_b32 s64, v254, 34
	v_readlane_b32 s65, v254, 35
	s_mov_b64 s[16:17], 0
	s_waitcnt vmcnt(0) lgkmcnt(0)
	v_pk_add_f32 v[164:165], v[164:165], v[138:139]
	ds_bpermute_b32 v138, v162, v92
	ds_bpermute_b32 v139, v162, v93
	v_pk_add_f32 v[166:167], v[166:167], v[156:157]
	v_pk_add_f32 v[172:173], v[172:173], v[228:229]
	v_pk_add_f32 v[174:175], v[174:175], v[230:231]
	v_pk_add_f32 v[178:179], v[178:179], v[234:235]
	v_pk_add_f32 v[176:177], v[176:177], v[232:233]
	v_pk_add_f32 v[182:183], v[182:183], v[238:239]
	v_pk_add_f32 v[180:181], v[180:181], v[236:237]
	global_store_dwordx4 v[152:153], v[164:167], off
	global_store_dwordx4 v[152:153], v[172:175], off offset:64
	global_store_dwordx4 v[152:153], v[176:179], off offset:512
	global_store_dwordx4 v[152:153], v[180:183], off offset:576
	v_pk_add_f32 v[166:167], v[186:187], v[242:243]
	v_pk_add_f32 v[164:165], v[184:185], v[240:241]
	v_pk_add_f32 v[172:173], v[188:189], v[244:245]
	v_add_co_u32_e32 v156, vcc, s40, v152
	v_pk_add_f32 v[174:175], v[190:191], v[246:247]
	v_pk_add_f32 v[178:179], v[194:195], v[250:251]
	v_pk_add_f32 v[176:177], v[192:193], v[248:249]
	global_store_dwordx4 v[136:137], v[164:167], off
	global_store_dwordx4 v[136:137], v[172:175], off offset:64
	global_store_dwordx4 v[136:137], v[176:179], off offset:512
	v_addc_co_u32_e32 v157, vcc, 0, v153, vcc
	ds_bpermute_b32 v172, v162, v98
	ds_bpermute_b32 v173, v162, v99
	v_pk_add_f32 v[134:135], v[134:135], v[252:253]
	global_load_dwordx4 v[164:167], v[156:157], off
	s_waitcnt lgkmcnt(2)
	v_pk_add_f32 v[132:133], v[132:133], v[138:139]
	global_store_dwordx4 v[136:137], v[132:135], off offset:576
	ds_bpermute_b32 v132, v162, v96
	ds_bpermute_b32 v133, v162, v97
	ds_bpermute_b32 v136, v162, v90
	ds_bpermute_b32 v137, v162, v91
	ds_bpermute_b32 v138, v162, v88
	ds_bpermute_b32 v139, v162, v89
	s_waitcnt lgkmcnt(6)
	v_pk_add_f32 v[134:135], v[198:199], v[172:173]
	global_load_dwordx4 v[172:175], v[156:157], off offset:64
	s_waitcnt lgkmcnt(4)
	v_pk_add_f32 v[132:133], v[196:197], v[132:133]
	global_store_dwordx4 v[208:209], v[132:135], off
	ds_bpermute_b32 v180, v162, v76
	ds_bpermute_b32 v182, v162, v78
	s_waitcnt lgkmcnt(4)
	v_pk_add_f32 v[134:135], v[202:203], v[136:137]
	ds_bpermute_b32 v136, v162, v86
	ds_bpermute_b32 v137, v162, v87
	s_waitcnt lgkmcnt(4)
	v_pk_add_f32 v[132:133], v[200:201], v[138:139]
	ds_bpermute_b32 v138, v162, v84
	ds_bpermute_b32 v139, v162, v85
	global_store_dwordx4 v[208:209], v[132:135], off offset:64
	global_load_dwordx4 v[132:135], v[156:157], off offset:512
	s_waitcnt lgkmcnt(2)
	v_pk_add_f32 v[178:179], v[206:207], v[136:137]
	ds_bpermute_b32 v183, v162, v79
	s_waitcnt lgkmcnt(1)
	v_pk_add_f32 v[176:177], v[204:205], v[138:139]
	global_load_dwordx4 v[136:139], v[156:157], off offset:576
	ds_bpermute_b32 v181, v162, v77
	global_store_dwordx4 v[208:209], v[176:179], off offset:512
	v_add_co_u32_e32 v204, vcc, s41, v152
	s_waitcnt lgkmcnt(1)
	v_pk_add_f32 v[178:179], v[214:215], v[182:183]
	s_waitcnt lgkmcnt(0)
	v_pk_add_f32 v[176:177], v[212:213], v[180:181]
	ds_bpermute_b32 v180, v162, v80
	ds_bpermute_b32 v181, v162, v81
	ds_bpermute_b32 v182, v162, v82
	ds_bpermute_b32 v183, v162, v83
	v_addc_co_u32_e32 v205, vcc, 0, v153, vcc
	global_store_dwordx4 v[208:209], v[176:179], off offset:576
	global_load_dwordx4 v[176:179], v[204:205], off
	s_waitcnt lgkmcnt(0)
	v_pk_add_f32 v[182:183], v[218:219], v[182:183]
	global_load_dwordx4 v[184:187], v[204:205], off offset:64
	v_pk_add_f32 v[180:181], v[216:217], v[180:181]
	ds_bpermute_b32 v188, v162, v74
	ds_bpermute_b32 v189, v162, v75
	global_store_dwordx4 v[154:155], v[180:183], off
	ds_bpermute_b32 v180, v162, v72
	ds_bpermute_b32 v181, v162, v73
	ds_bpermute_b32 v192, v162, v68
	s_waitcnt lgkmcnt(3)
	v_pk_add_f32 v[182:183], v[222:223], v[188:189]
	global_load_dwordx4 v[188:191], v[204:205], off offset:512
	ds_bpermute_b32 v193, v162, v69
	s_waitcnt lgkmcnt(2)
	v_pk_add_f32 v[180:181], v[220:221], v[180:181]
	ds_bpermute_b32 v194, v162, v70
	ds_bpermute_b32 v195, v162, v71
	global_store_dwordx4 v[154:155], v[180:183], off offset:64
	global_load_dwordx4 v[180:183], v[204:205], off offset:576
	ds_bpermute_b32 v200, v162, v64
	ds_bpermute_b32 v196, v162, v66
	ds_bpermute_b32 v197, v162, v67
	ds_bpermute_b32 v201, v162, v65
	v_add_co_u32_e32 v206, vcc, s42, v152
	s_waitcnt lgkmcnt(4)
	v_pk_add_f32 v[194:195], v[226:227], v[194:195]
	v_pk_add_f32 v[192:193], v[224:225], v[192:193]
	v_addc_co_u32_e32 v207, vcc, 0, v153, vcc
	global_store_dwordx4 v[154:155], v[192:195], off offset:512
	global_load_dwordx4 v[192:195], v[206:207], off
	s_waitcnt lgkmcnt(1)
	v_pk_add_f32 v[130:131], v[130:131], v[196:197]
	s_waitcnt lgkmcnt(0)
	v_pk_add_f32 v[128:129], v[128:129], v[200:201]
	global_load_dwordx4 v[196:199], v[206:207], off offset:64
	ds_bpermute_b32 v202, v162, v62
	ds_bpermute_b32 v203, v162, v63
	global_store_dwordx4 v[154:155], v[128:131], off offset:576
	ds_bpermute_b32 v128, v162, v60
	ds_bpermute_b32 v129, v162, v61
	ds_bpermute_b32 v208, v162, v58
	ds_bpermute_b32 v209, v162, v59
	s_waitcnt vmcnt(18) lgkmcnt(4)
	v_pk_add_f32 v[130:131], v[166:167], v[202:203]
	ds_bpermute_b32 v154, v162, v56
	global_load_dwordx4 v[200:203], v[206:207], off offset:512
	ds_bpermute_b32 v155, v162, v57
	s_waitcnt lgkmcnt(4)
	v_pk_add_f32 v[128:129], v[164:165], v[128:129]
	global_load_dwordx4 v[164:167], v[206:207], off offset:576
	ds_bpermute_b32 v212, v162, v44
	global_store_dwordx4 v[156:157], v[128:131], off
	ds_bpermute_b32 v214, v162, v46
	ds_bpermute_b32 v215, v162, v47
	s_waitcnt vmcnt(19) lgkmcnt(5)
	v_pk_add_f32 v[130:131], v[174:175], v[208:209]
	v_add_co_u32_e32 v208, vcc, s43, v152
	s_waitcnt lgkmcnt(3)
	v_pk_add_f32 v[128:129], v[172:173], v[154:155]
	v_addc_co_u32_e32 v209, vcc, 0, v153, vcc
	global_store_dwordx4 v[156:157], v[128:131], off offset:64
	ds_bpermute_b32 v172, v162, v48
	ds_bpermute_b32 v173, v162, v49
	global_load_dwordx4 v[128:131], v[208:209], off
	global_load_dwordx4 v[152:155], v[208:209], off offset:64
	ds_bpermute_b32 v174, v162, v50
	ds_bpermute_b32 v175, v162, v51
	ds_bpermute_b32 v213, v162, v45
	s_waitcnt vmcnt(19) lgkmcnt(3)
	v_pk_add_f32 v[132:133], v[132:133], v[172:173]
	ds_bpermute_b32 v172, v162, v54
	ds_bpermute_b32 v173, v162, v55
	s_waitcnt lgkmcnt(3)
	v_pk_add_f32 v[134:135], v[134:135], v[174:175]
	global_store_dwordx4 v[156:157], v[132:135], off offset:512
	s_waitcnt vmcnt(16) lgkmcnt(0)
	v_pk_add_f32 v[174:175], v[178:179], v[172:173]
	v_pk_add_f32 v[134:135], v[138:139], v[214:215]
	v_pk_add_f32 v[132:133], v[136:137], v[212:213]
	global_store_dwordx4 v[156:157], v[132:135], off offset:576
	global_load_dwordx4 v[132:135], v[208:209], off offset:512
	ds_bpermute_b32 v156, v162, v52
	global_load_dwordx4 v[136:139], v[208:209], off offset:576
	ds_bpermute_b32 v157, v162, v53
	ds_bpermute_b32 v212, v162, v40
	ds_bpermute_b32 v214, v162, v42
	ds_bpermute_b32 v215, v162, v43
	ds_bpermute_b32 v213, v162, v41
	s_waitcnt lgkmcnt(4)
	v_pk_add_f32 v[172:173], v[176:177], v[156:157]
	global_store_dwordx4 v[204:205], v[172:175], off
	ds_bpermute_b32 v156, v162, v32
	ds_bpermute_b32 v157, v162, v33
	s_waitcnt vmcnt(19) lgkmcnt(3)
	v_pk_add_f32 v[174:175], v[186:187], v[214:215]
	s_waitcnt lgkmcnt(2)
	v_pk_add_f32 v[172:173], v[184:185], v[212:213]
	global_store_dwordx4 v[204:205], v[172:175], off offset:64
	ds_bpermute_b32 v172, v162, v34
	ds_bpermute_b32 v173, v162, v35
	ds_bpermute_b32 v176, v162, v28
	ds_bpermute_b32 v178, v162, v30
	ds_bpermute_b32 v179, v162, v31
	ds_bpermute_b32 v177, v162, v29
	s_waitcnt vmcnt(18) lgkmcnt(4)
	v_pk_add_f32 v[174:175], v[190:191], v[172:173]
	v_pk_add_f32 v[172:173], v[188:189], v[156:157]
	global_store_dwordx4 v[204:205], v[172:175], off offset:512
	ds_bpermute_b32 v156, v162, v36
	ds_bpermute_b32 v157, v162, v37
	s_waitcnt vmcnt(17) lgkmcnt(3)
	v_pk_add_f32 v[174:175], v[182:183], v[178:179]
	s_waitcnt lgkmcnt(2)
	v_pk_add_f32 v[172:173], v[180:181], v[176:177]
	global_store_dwordx4 v[204:205], v[172:175], off offset:576
	ds_bpermute_b32 v172, v162, v38
	ds_bpermute_b32 v173, v162, v39
	ds_bpermute_b32 v176, v162, v24
	ds_bpermute_b32 v178, v162, v26
	ds_bpermute_b32 v179, v162, v27
	ds_bpermute_b32 v177, v162, v25
	s_waitcnt vmcnt(16) lgkmcnt(4)
	v_pk_add_f32 v[174:175], v[194:195], v[172:173]
	v_pk_add_f32 v[172:173], v[192:193], v[156:157]
	global_store_dwordx4 v[206:207], v[172:175], off
	ds_bpermute_b32 v156, v162, v16
	ds_bpermute_b32 v157, v162, v17
	s_waitcnt vmcnt(16) lgkmcnt(3)
	v_pk_add_f32 v[174:175], v[198:199], v[178:179]
	s_waitcnt lgkmcnt(2)
	v_pk_add_f32 v[172:173], v[196:197], v[176:177]
	ds_bpermute_b32 v176, v162, v12
	ds_bpermute_b32 v178, v162, v14
	ds_bpermute_b32 v179, v162, v15
	ds_bpermute_b32 v177, v162, v13
	global_store_dwordx4 v[206:207], v[172:175], off offset:64
	ds_bpermute_b32 v172, v162, v18
	ds_bpermute_b32 v173, v162, v19
	s_waitcnt vmcnt(14) lgkmcnt(3)
	v_pk_add_f32 v[166:167], v[166:167], v[178:179]
	s_waitcnt lgkmcnt(2)
	v_pk_add_f32 v[164:165], v[164:165], v[176:177]
	global_store_dwordx4 v[206:207], v[164:167], off offset:576
	ds_bpermute_b32 v164, v162, v22
	s_waitcnt lgkmcnt(1)
	v_pk_add_f32 v[174:175], v[202:203], v[172:173]
	v_pk_add_f32 v[172:173], v[200:201], v[156:157]
	ds_bpermute_b32 v156, v162, v20
	ds_bpermute_b32 v157, v162, v21
	ds_bpermute_b32 v165, v162, v23
	global_store_dwordx4 v[206:207], v[172:175], off offset:512
	ds_bpermute_b32 v166, v162, v8
	ds_bpermute_b32 v172, v162, v10
	ds_bpermute_b32 v173, v162, v11
	ds_bpermute_b32 v167, v162, v9
	s_waitcnt vmcnt(13) lgkmcnt(4)
	v_pk_add_f32 v[130:131], v[130:131], v[164:165]
	v_pk_add_f32 v[128:129], v[128:129], v[156:157]
	global_store_dwordx4 v[208:209], v[128:131], off
	s_waitcnt vmcnt(13) lgkmcnt(1)
	s_nop 0
	v_pk_add_f32 v[130:131], v[154:155], v[172:173]
	s_waitcnt lgkmcnt(0)
	v_pk_add_f32 v[128:129], v[152:153], v[166:167]
	global_store_dwordx4 v[208:209], v[128:131], off offset:64
	ds_bpermute_b32 v128, v162, v4
	ds_bpermute_b32 v129, v162, v5
	ds_bpermute_b32 v130, v162, v6
	ds_bpermute_b32 v131, v162, v7
	ds_bpermute_b32 v152, v162, v0
	ds_bpermute_b32 v154, v162, v2
	ds_bpermute_b32 v155, v162, v3
	ds_bpermute_b32 v153, v162, v1
	s_waitcnt vmcnt(11) lgkmcnt(4)
	v_pk_add_f32 v[130:131], v[134:135], v[130:131]
	v_pk_add_f32 v[128:129], v[132:133], v[128:129]
	global_store_dwordx4 v[208:209], v[128:131], off offset:512
	s_waitcnt vmcnt(11) lgkmcnt(1)
	s_nop 0
	v_pk_add_f32 v[130:131], v[138:139], v[154:155]
	s_waitcnt lgkmcnt(0)
	v_pk_add_f32 v[128:129], v[136:137], v[152:153]
	global_store_dwordx4 v[208:209], v[128:131], off offset:576
